# epilogue loads of phases 5a/5b/6 issued up front (row loops unrolled) on top of the fused P6+P7
# speedup vs baseline: 1.0094x; 1.0094x over previous
; __device__ __forceinline__ int ltid() { int t = threadIdx.x; asm volatile("" : "+v"(t)); return t; }
; __device__ __forceinline__ void stage_acc(f32x16 (&acc)[2][2], float* sC) {
;   const int tid__ = ltid(); const int lane = tid__ & 63, wave = tid__ >> 6;
;   const int wm = wave >> 1, wn = wave & 1, l31 = lane & 31, hf = lane >> 5;
;   float* base = sC + (wm * 64 + 4 * hf) * 132 + wn * 64 + l31;
; #pragma unroll
;   for (int mi = 0; mi < 2; ++mi)
; #pragma unroll
;     for (int ni = 0; ni < 2; ++ni)
; #pragma unroll
;       for (int r = 0; r < 16; ++r) base[(mi * 32 + 8 * (r >> 2) + (r & 3)) * 132 + ni * 32] = acc[mi][ni][r];
;   __syncthreads();
; __device__ __forceinline__ void phase5(const Params& p, unsigned char* smem) {
;     ...
;     epilogue_rows(acc, m0, n0, smem, [&](int m, int n, float4 a, float4 b) {
;       uint4 g = *(const uint4*)(SGA + (size_t)m * 1024 + n);
.LBB0_403:
	s_waitcnt vmcnt(7)
	v_mov_b32_e32 v64, v218
	s_mov_b32 s14, 0
	v_and_b32_e32 v65, 64, v64
	v_and_b32_e32 v66, 31, v64
	v_lshrrev_b32_e32 v67, 1, v64
	v_lshrrev_b32_e32 v64, 3, v64
	v_and_b32_e32 v64, 4, v64
	v_and_or_b32 v64, v67, s23, v64
	v_mul_lo_u32 v64, v64, s24
	v_add_u32_e32 v64, 16, v64
	v_lshlrev_b32_e32 v65, 2, v65
	v_lshlrev_b32_e32 v66, 2, v66
	v_add3_u32 v64, v64, v65, v66
	ds_write2_b32 v64, v48, v32 offset1:32
	ds_write2_b32 v64, v49, v33 offset0:132 offset1:164
	v_add_u32_e32 v32, 0x400, v64
	ds_write2_b32 v32, v50, v34 offset0:8 offset1:40
	ds_write2_b32 v32, v51, v35 offset0:140 offset1:172
	v_add_u32_e32 v32, 0x1000, v64
	ds_write2_b32 v32, v52, v36 offset0:32 offset1:64
	ds_write2_b32 v32, v53, v37 offset0:164 offset1:196
	v_add_u32_e32 v32, 0x1400, v64
	ds_write2_b32 v32, v54, v38 offset0:40 offset1:72
	ds_write2_b32 v32, v55, v39 offset0:172 offset1:204
	v_add_u32_e32 v32, 0x2000, v64
	ds_write2_b32 v32, v56, v40 offset0:64 offset1:96
	ds_write2_b32 v32, v57, v41 offset0:196 offset1:228
	v_add_u32_e32 v32, 0x2400, v64
	ds_write2_b32 v32, v58, v42 offset0:72 offset1:104
	ds_write2_b32 v32, v59, v43 offset0:204 offset1:236
	v_add_u32_e32 v32, 0x3000, v64
	ds_write2_b32 v32, v60, v44 offset0:96 offset1:128
	v_add_u32_e32 v32, 0x3200, v64
	ds_write2_b32 v32, v61, v45 offset0:100 offset1:132
	v_add_u32_e32 v32, 0x3400, v64
	ds_write2_b32 v32, v62, v46 offset0:104 offset1:136
	v_add_u32_e32 v32, 0x3600, v64
	ds_write2_b32 v32, v63, v47 offset0:108 offset1:140
	v_add_u32_e32 v32, 0x4000, v64
	ds_write2_b32 v32, v16, v0 offset0:128 offset1:160
	v_add_u32_e32 v0, 0x4400, v64
	ds_write2_b32 v0, v17, v1 offset0:4 offset1:36
	ds_write2_b32 v0, v18, v2 offset0:136 offset1:168
	v_add_u32_e32 v0, 0x4800, v64
	ds_write2_b32 v0, v19, v3 offset0:12 offset1:44
	v_add_u32_e32 v0, 0x5000, v64
	ds_write2_b32 v0, v20, v4 offset0:160 offset1:192
	v_add_u32_e32 v0, 0x5400, v64
	ds_write2_b32 v0, v21, v5 offset0:36 offset1:68
	ds_write2_b32 v0, v22, v6 offset0:168 offset1:200
	v_add_u32_e32 v0, 0x5800, v64
	ds_write2_b32 v0, v23, v7 offset0:44 offset1:76
	v_add_u32_e32 v0, 0x6000, v64
	ds_write2_b32 v0, v24, v8 offset0:192 offset1:224
	v_add_u32_e32 v0, 0x6400, v64
	ds_write2_b32 v0, v25, v9 offset0:68 offset1:100
	ds_write2_b32 v0, v26, v10 offset0:200 offset1:232
	v_add_u32_e32 v0, 0x6800, v64
	ds_write2_b32 v0, v27, v11 offset0:76 offset1:108
	v_add_u32_e32 v0, 0x7200, v64
	ds_write2_b32 v0, v28, v12 offset0:96 offset1:128
	v_add_u32_e32 v0, 0x7400, v64
	ds_write2_b32 v0, v29, v13 offset0:100 offset1:132
	v_add_u32_e32 v0, 0x7600, v64
	ds_write2_b32 v0, v30, v14 offset0:104 offset1:136
	v_add_u32_e32 v0, 0x7800, v64
	v_mov_b32_e32 v1, v218
	ds_write2_b32 v0, v31, v15 offset0:108 offset1:140
	v_lshlrev_b32_e32 v0, 3, v1
	v_and_b32_e32 v2, 0x78, v0
	v_or_b32_e32 v2, s27, v2
	v_ashrrev_i32_e32 v3, 31, v2
	v_lshlrev_b64 v[4:5], 1, v[2:3]
	v_lshl_add_u64 v[2:3], s[8:9], 0, v[4:5]
	s_movk_i32 s74, 0x0
	v_add_u32_e32 v10, s74, v1
	v_ashrrev_i32_e32 v11, 4, v10
	v_add_u32_e32 v6, s26, v11
	v_ashrrev_i32_e32 v7, 31, v6
	v_lshlrev_b64 v[18:19], 11, v[6:7]
	v_lshl_add_u64 v[6:7], v[2:3], 0, v[18:19]
	global_load_dwordx4 v[140:143], v[6:7], off
	v_add_u32_e32 v10, 0x100, v10
	v_ashrrev_i32_e32 v28, 4, v10
	v_add_u32_e32 v20, s26, v28
	v_ashrrev_i32_e32 v21, 31, v20
	v_lshlrev_b64 v[20:21], 11, v[20:21]
	v_lshl_add_u64 v[22:23], v[2:3], 0, v[20:21]
	global_load_dwordx4 v[144:147], v[22:23], off
	s_movk_i32 s74, 0x200
	v_add_u32_e32 v10, s74, v1
	v_ashrrev_i32_e32 v11, 4, v10
	v_add_u32_e32 v6, s26, v11
	v_ashrrev_i32_e32 v7, 31, v6
	v_lshlrev_b64 v[18:19], 11, v[6:7]
	v_lshl_add_u64 v[6:7], v[2:3], 0, v[18:19]
	global_load_dwordx4 v[148:151], v[6:7], off
	v_add_u32_e32 v10, 0x100, v10
	v_ashrrev_i32_e32 v28, 4, v10
	v_add_u32_e32 v20, s26, v28
	v_ashrrev_i32_e32 v21, 31, v20
	v_lshlrev_b64 v[20:21], 11, v[20:21]
	v_lshl_add_u64 v[22:23], v[2:3], 0, v[20:21]
	global_load_dwordx4 v[152:155], v[22:23], off
	s_movk_i32 s74, 0x400
	v_add_u32_e32 v10, s74, v1
	v_ashrrev_i32_e32 v11, 4, v10
	v_add_u32_e32 v6, s26, v11
	v_ashrrev_i32_e32 v7, 31, v6
	v_lshlrev_b64 v[18:19], 11, v[6:7]
	v_lshl_add_u64 v[6:7], v[2:3], 0, v[18:19]
	global_load_dwordx4 v[156:159], v[6:7], off
	v_add_u32_e32 v10, 0x100, v10
	v_ashrrev_i32_e32 v28, 4, v10
	v_add_u32_e32 v20, s26, v28
	v_ashrrev_i32_e32 v21, 31, v20
	v_lshlrev_b64 v[20:21], 11, v[20:21]
	v_lshl_add_u64 v[22:23], v[2:3], 0, v[20:21]
	global_load_dwordx4 v[160:163], v[22:23], off
	s_movk_i32 s74, 0x600
	v_add_u32_e32 v10, s74, v1
	v_ashrrev_i32_e32 v11, 4, v10
	v_add_u32_e32 v6, s26, v11
	v_ashrrev_i32_e32 v7, 31, v6
	v_lshlrev_b64 v[18:19], 11, v[6:7]
	v_lshl_add_u64 v[6:7], v[2:3], 0, v[18:19]
	global_load_dwordx4 v[164:167], v[6:7], off
	v_add_u32_e32 v10, 0x100, v10
	v_ashrrev_i32_e32 v28, 4, v10
	v_add_u32_e32 v20, s26, v28
	v_ashrrev_i32_e32 v21, 31, v20
	v_lshlrev_b64 v[20:21], 11, v[20:21]
	v_lshl_add_u64 v[22:23], v[2:3], 0, v[20:21]
	global_load_dwordx4 v[168:171], v[22:23], off
	s_waitcnt lgkmcnt(0)
	s_barrier
	s_nop 0
	v_lshlrev_b32_e32 v0, 3, v1
	v_and_b32_e32 v2, 0x78, v0
	v_lshl_add_u32 v0, v2, 2, 16
	v_or_b32_e32 v2, s27, v2
	v_ashrrev_i32_e32 v3, 31, v2
	v_lshlrev_b64 v[4:5], 1, v[2:3]
	v_lshl_add_u64 v[2:3], s[8:9], 0, v[4:5]
	v_lshl_add_u64 v[4:5], s[6:7], 0, v[4:5]
; __device__ __forceinline__ float bflo(unsigned v) { return __uint_as_float(v << 16); }
; __device__ __forceinline__ float bfhi(unsigned v) { return __uint_as_float(v & 0xffff0000u); }
; __device__ __forceinline__ uint4 pack8(float4 a, float4 b) { uint4 o; o.x = cvtpk(a.x, a.y); o.y = cvtpk(a.z, a.w); o.z = cvtpk(b.x, b.y); o.w = cvtpk(b.z, b.w); return o; }
; __device__ __forceinline__ void phase5(const Params& p, unsigned char* smem) {
;     ...
;     epilogue_rows(acc, m0, n0, smem, [&](int m, int n, float4 a, float4 b) {
;       uint4 g = *(const uint4*)(SGA + (size_t)m * 1024 + n);
;       a.x *= bflo(g.x); a.y *= bfhi(g.x); a.z *= bflo(g.y); a.w *= bfhi(g.y); b.x *= bflo(g.z); b.y *= bfhi(g.z); b.z *= bflo(g.w); b.w *= bfhi(g.w);
;       *(uint4*)(MERGED + (size_t)m * 1024 + n) = pack8(a, b);
;     });
.LBB0_404:
	s_waitcnt vmcnt(0)
	v_add_u32_e32 v10, s14, v1
	v_ashrrev_i32_e32 v11, 4, v10
	v_add_u32_e32 v6, s26, v11
	v_ashrrev_i32_e32 v7, 31, v6
	v_lshlrev_b64 v[18:19], 11, v[6:7]
	v_lshl_add_u64 v[6:7], v[2:3], 0, v[18:19]
	v_mov_b32_e32 v6, v140
	v_mov_b32_e32 v7, v141
	v_mov_b32_e32 v8, v142
	v_mov_b32_e32 v9, v143
	v_add_u32_e32 v10, 0x100, v10
	v_mad_u64_u32 v[14:15], s[16:17], v11, s24, v[0:1]
	v_ashrrev_i32_e32 v28, 4, v10
	ds_read_b128 v[10:13], v14
	ds_read_b128 v[14:17], v14 offset:16
	v_add_u32_e32 v20, s26, v28
	v_ashrrev_i32_e32 v21, 31, v20
	v_lshl_add_u64 v[18:19], v[4:5], 0, v[18:19]
	v_lshlrev_b64 v[20:21], 11, v[20:21]
	v_lshl_add_u64 v[22:23], v[2:3], 0, v[20:21]
	s_addk_i32 s14, 0x200
	s_cmpk_lg_i32 s14, 0x800
	v_lshlrev_b32_e32 v24, 16, v6
	v_and_b32_e32 v25, 0xffff0000, v6
	v_lshlrev_b32_e32 v6, 16, v7
	v_and_b32_e32 v7, 0xffff0000, v7
	v_lshlrev_b32_e32 v26, 16, v8
	v_and_b32_e32 v27, 0xffff0000, v8
	v_lshlrev_b32_e32 v8, 16, v9
	v_and_b32_e32 v9, 0xffff0000, v9
	s_waitcnt lgkmcnt(1)
	v_pk_mul_f32 v[10:11], v[10:11], v[24:25]
	v_pk_mul_f32 v[12:13], v[12:13], v[6:7]
	s_waitcnt lgkmcnt(0)
	v_pk_mul_f32 v[14:15], v[14:15], v[26:27]
	v_pk_mul_f32 v[16:17], v[16:17], v[8:9]
	v_cvt_pk_bf16_f32 v6, v10, v11
	v_cvt_pk_bf16_f32 v7, v12, v13
	v_cvt_pk_bf16_f32 v8, v14, v15
	v_cvt_pk_bf16_f32 v9, v16, v17
	global_store_dwordx4 v[18:19], v[6:9], off sc1
	s_nop 1
	v_mov_b32_e32 v6, v144
	v_mov_b32_e32 v7, v145
	v_mov_b32_e32 v8, v146
	v_mov_b32_e32 v9, v147
	v_mad_u64_u32 v[14:15], s[16:17], v28, s24, v[0:1]
	ds_read_b128 v[10:13], v14
	ds_read_b128 v[14:17], v14 offset:16
	v_lshl_add_u64 v[18:19], v[4:5], 0, v[20:21]
	v_lshlrev_b32_e32 v20, 16, v6
	v_and_b32_e32 v21, 0xffff0000, v6
	v_lshlrev_b32_e32 v6, 16, v7
	v_and_b32_e32 v7, 0xffff0000, v7
	v_lshlrev_b32_e32 v22, 16, v8
	v_and_b32_e32 v23, 0xffff0000, v8
	v_lshlrev_b32_e32 v8, 16, v9
	v_and_b32_e32 v9, 0xffff0000, v9
	s_waitcnt lgkmcnt(1)
	v_pk_mul_f32 v[10:11], v[10:11], v[20:21]
	v_pk_mul_f32 v[12:13], v[12:13], v[6:7]
	s_waitcnt lgkmcnt(0)
	v_pk_mul_f32 v[14:15], v[14:15], v[22:23]
	v_pk_mul_f32 v[16:17], v[16:17], v[8:9]
	v_cvt_pk_bf16_f32 v6, v10, v11
	v_cvt_pk_bf16_f32 v7, v12, v13
	v_cvt_pk_bf16_f32 v8, v14, v15
	v_cvt_pk_bf16_f32 v9, v16, v17
	global_store_dwordx4 v[18:19], v[6:9], off sc1
	v_add_u32_e32 v10, s14, v1
	v_ashrrev_i32_e32 v11, 4, v10
	v_add_u32_e32 v6, s26, v11
	v_ashrrev_i32_e32 v7, 31, v6
	v_lshlrev_b64 v[18:19], 11, v[6:7]
	v_lshl_add_u64 v[6:7], v[2:3], 0, v[18:19]
	v_mov_b32_e32 v6, v148
	v_mov_b32_e32 v7, v149
	v_mov_b32_e32 v8, v150
	v_mov_b32_e32 v9, v151
	v_add_u32_e32 v10, 0x100, v10
	v_mad_u64_u32 v[14:15], s[16:17], v11, s24, v[0:1]
	v_ashrrev_i32_e32 v28, 4, v10
	ds_read_b128 v[10:13], v14
	ds_read_b128 v[14:17], v14 offset:16
	v_add_u32_e32 v20, s26, v28
	v_ashrrev_i32_e32 v21, 31, v20
	v_lshl_add_u64 v[18:19], v[4:5], 0, v[18:19]
	v_lshlrev_b64 v[20:21], 11, v[20:21]
	v_lshl_add_u64 v[22:23], v[2:3], 0, v[20:21]
	s_addk_i32 s14, 0x200
	s_cmpk_lg_i32 s14, 0x800
	v_lshlrev_b32_e32 v24, 16, v6
	v_and_b32_e32 v25, 0xffff0000, v6
	v_lshlrev_b32_e32 v6, 16, v7
	v_and_b32_e32 v7, 0xffff0000, v7
	v_lshlrev_b32_e32 v26, 16, v8
	v_and_b32_e32 v27, 0xffff0000, v8
	v_lshlrev_b32_e32 v8, 16, v9
	v_and_b32_e32 v9, 0xffff0000, v9
	s_waitcnt lgkmcnt(1)
	v_pk_mul_f32 v[10:11], v[10:11], v[24:25]
	v_pk_mul_f32 v[12:13], v[12:13], v[6:7]
	s_waitcnt lgkmcnt(0)
	v_pk_mul_f32 v[14:15], v[14:15], v[26:27]
	v_pk_mul_f32 v[16:17], v[16:17], v[8:9]
	v_cvt_pk_bf16_f32 v6, v10, v11
	v_cvt_pk_bf16_f32 v7, v12, v13
	v_cvt_pk_bf16_f32 v8, v14, v15
	v_cvt_pk_bf16_f32 v9, v16, v17
	global_store_dwordx4 v[18:19], v[6:9], off sc1
	s_nop 1
	v_mov_b32_e32 v6, v152
	v_mov_b32_e32 v7, v153
	v_mov_b32_e32 v8, v154
	v_mov_b32_e32 v9, v155
	v_mad_u64_u32 v[14:15], s[16:17], v28, s24, v[0:1]
	ds_read_b128 v[10:13], v14
	ds_read_b128 v[14:17], v14 offset:16
	v_lshl_add_u64 v[18:19], v[4:5], 0, v[20:21]
	v_lshlrev_b32_e32 v20, 16, v6
	v_and_b32_e32 v21, 0xffff0000, v6
	v_lshlrev_b32_e32 v6, 16, v7
	v_and_b32_e32 v7, 0xffff0000, v7
	v_lshlrev_b32_e32 v22, 16, v8
	v_and_b32_e32 v23, 0xffff0000, v8
	v_lshlrev_b32_e32 v8, 16, v9
	v_and_b32_e32 v9, 0xffff0000, v9
	s_waitcnt lgkmcnt(1)
	v_pk_mul_f32 v[10:11], v[10:11], v[20:21]
	v_pk_mul_f32 v[12:13], v[12:13], v[6:7]
	s_waitcnt lgkmcnt(0)
; __device__ __forceinline__ float bflo(unsigned v) { return __uint_as_float(v << 16); }
; __device__ __forceinline__ float bfhi(unsigned v) { return __uint_as_float(v & 0xffff0000u); }
; __device__ __forceinline__ uint4 pack8(float4 a, float4 b) { uint4 o; o.x = cvtpk(a.x, a.y); o.y = cvtpk(a.z, a.w); o.z = cvtpk(b.x, b.y); o.w = cvtpk(b.z, b.w); return o; }
; template <class Epi>
; __device__ __forceinline__ void epilogue_rows(f32x16 (&acc)[2][2], int m0, int n0, unsigned char* smem, Epi epi) {
;     ...
;   for (int it = 0; it < 8; ++it) {
;     int idx = tid + 256 * it; int r = idx >> 4, c8 = (idx & 15) * 8;
;     float4 a = *(const float4*)(sC + r * 132 + c8), b = *(const float4*)(sC + r * 132 + c8 + 4);
;     epi(m0 + r, n0 + c8, a, b);
;   }
; __device__ __forceinline__ void phase5(const Params& p, unsigned char* smem) {
;     ...
;     epilogue_rows(acc, m0, n0, smem, [&](int m, int n, float4 a, float4 b) {
;       uint4 g = *(const uint4*)(SGA + (size_t)m * 1024 + n);
;       a.x *= bflo(g.x); a.y *= bfhi(g.x); a.z *= bflo(g.y); a.w *= bfhi(g.y); b.x *= bflo(g.z); b.y *= bfhi(g.z); b.z *= bflo(g.w); b.w *= bfhi(g.w);
;       *(uint4*)(MERGED + (size_t)m * 1024 + n) = pack8(a, b);
;     });
	v_pk_mul_f32 v[14:15], v[14:15], v[22:23]
	v_pk_mul_f32 v[16:17], v[16:17], v[8:9]
	v_cvt_pk_bf16_f32 v6, v10, v11
	v_cvt_pk_bf16_f32 v7, v12, v13
	v_cvt_pk_bf16_f32 v8, v14, v15
	v_cvt_pk_bf16_f32 v9, v16, v17
	global_store_dwordx4 v[18:19], v[6:9], off sc1
	v_add_u32_e32 v10, s14, v1
	v_ashrrev_i32_e32 v11, 4, v10
	v_add_u32_e32 v6, s26, v11
	v_ashrrev_i32_e32 v7, 31, v6
	v_lshlrev_b64 v[18:19], 11, v[6:7]
	v_lshl_add_u64 v[6:7], v[2:3], 0, v[18:19]
	v_mov_b32_e32 v6, v156
	v_mov_b32_e32 v7, v157
	v_mov_b32_e32 v8, v158
	v_mov_b32_e32 v9, v159
	v_add_u32_e32 v10, 0x100, v10
	v_mad_u64_u32 v[14:15], s[16:17], v11, s24, v[0:1]
	v_ashrrev_i32_e32 v28, 4, v10
	ds_read_b128 v[10:13], v14
	ds_read_b128 v[14:17], v14 offset:16
	v_add_u32_e32 v20, s26, v28
	v_ashrrev_i32_e32 v21, 31, v20
	v_lshl_add_u64 v[18:19], v[4:5], 0, v[18:19]
	v_lshlrev_b64 v[20:21], 11, v[20:21]
	v_lshl_add_u64 v[22:23], v[2:3], 0, v[20:21]
	s_addk_i32 s14, 0x200
	s_cmpk_lg_i32 s14, 0x800
	v_lshlrev_b32_e32 v24, 16, v6
	v_and_b32_e32 v25, 0xffff0000, v6
	v_lshlrev_b32_e32 v6, 16, v7
	v_and_b32_e32 v7, 0xffff0000, v7
	v_lshlrev_b32_e32 v26, 16, v8
	v_and_b32_e32 v27, 0xffff0000, v8
	v_lshlrev_b32_e32 v8, 16, v9
	v_and_b32_e32 v9, 0xffff0000, v9
	s_waitcnt lgkmcnt(1)
	v_pk_mul_f32 v[10:11], v[10:11], v[24:25]
	v_pk_mul_f32 v[12:13], v[12:13], v[6:7]
	s_waitcnt lgkmcnt(0)
	v_pk_mul_f32 v[14:15], v[14:15], v[26:27]
	v_pk_mul_f32 v[16:17], v[16:17], v[8:9]
	v_cvt_pk_bf16_f32 v6, v10, v11
	v_cvt_pk_bf16_f32 v7, v12, v13
	v_cvt_pk_bf16_f32 v8, v14, v15
	v_cvt_pk_bf16_f32 v9, v16, v17
	global_store_dwordx4 v[18:19], v[6:9], off sc1
	s_nop 1
	v_mov_b32_e32 v6, v160
	v_mov_b32_e32 v7, v161
	v_mov_b32_e32 v8, v162
	v_mov_b32_e32 v9, v163
	v_mad_u64_u32 v[14:15], s[16:17], v28, s24, v[0:1]
	ds_read_b128 v[10:13], v14
	ds_read_b128 v[14:17], v14 offset:16
	v_lshl_add_u64 v[18:19], v[4:5], 0, v[20:21]
	v_lshlrev_b32_e32 v20, 16, v6
	v_and_b32_e32 v21, 0xffff0000, v6
	v_lshlrev_b32_e32 v6, 16, v7
	v_and_b32_e32 v7, 0xffff0000, v7
	v_lshlrev_b32_e32 v22, 16, v8
	v_and_b32_e32 v23, 0xffff0000, v8
	v_lshlrev_b32_e32 v8, 16, v9
	v_and_b32_e32 v9, 0xffff0000, v9
	s_waitcnt lgkmcnt(1)
	v_pk_mul_f32 v[10:11], v[10:11], v[20:21]
	v_pk_mul_f32 v[12:13], v[12:13], v[6:7]
	s_waitcnt lgkmcnt(0)
	v_pk_mul_f32 v[14:15], v[14:15], v[22:23]
	v_pk_mul_f32 v[16:17], v[16:17], v[8:9]
	v_cvt_pk_bf16_f32 v6, v10, v11
	v_cvt_pk_bf16_f32 v7, v12, v13
	v_cvt_pk_bf16_f32 v8, v14, v15
	v_cvt_pk_bf16_f32 v9, v16, v17
	global_store_dwordx4 v[18:19], v[6:9], off sc1
	v_add_u32_e32 v10, s14, v1
	v_ashrrev_i32_e32 v11, 4, v10
	v_add_u32_e32 v6, s26, v11
	v_ashrrev_i32_e32 v7, 31, v6
	v_lshlrev_b64 v[18:19], 11, v[6:7]
	v_lshl_add_u64 v[6:7], v[2:3], 0, v[18:19]
	v_mov_b32_e32 v6, v164
	v_mov_b32_e32 v7, v165
	v_mov_b32_e32 v8, v166
	v_mov_b32_e32 v9, v167
	v_add_u32_e32 v10, 0x100, v10
	v_mad_u64_u32 v[14:15], s[16:17], v11, s24, v[0:1]
	v_ashrrev_i32_e32 v28, 4, v10
	ds_read_b128 v[10:13], v14
	ds_read_b128 v[14:17], v14 offset:16
	v_add_u32_e32 v20, s26, v28
	v_ashrrev_i32_e32 v21, 31, v20
	v_lshl_add_u64 v[18:19], v[4:5], 0, v[18:19]
	v_lshlrev_b64 v[20:21], 11, v[20:21]
	v_lshl_add_u64 v[22:23], v[2:3], 0, v[20:21]
	s_addk_i32 s14, 0x200
	s_cmpk_lg_i32 s14, 0x800
	v_lshlrev_b32_e32 v24, 16, v6
	v_and_b32_e32 v25, 0xffff0000, v6
	v_lshlrev_b32_e32 v6, 16, v7
	v_and_b32_e32 v7, 0xffff0000, v7
	v_lshlrev_b32_e32 v26, 16, v8
	v_and_b32_e32 v27, 0xffff0000, v8
	v_lshlrev_b32_e32 v8, 16, v9
	v_and_b32_e32 v9, 0xffff0000, v9
	s_waitcnt lgkmcnt(1)
	v_pk_mul_f32 v[10:11], v[10:11], v[24:25]
	v_pk_mul_f32 v[12:13], v[12:13], v[6:7]
	s_waitcnt lgkmcnt(0)
	v_pk_mul_f32 v[14:15], v[14:15], v[26:27]
	v_pk_mul_f32 v[16:17], v[16:17], v[8:9]
	v_cvt_pk_bf16_f32 v6, v10, v11
	v_cvt_pk_bf16_f32 v7, v12, v13
	v_cvt_pk_bf16_f32 v8, v14, v15
	v_cvt_pk_bf16_f32 v9, v16, v17
	global_store_dwordx4 v[18:19], v[6:9], off sc1
	s_nop 1
	v_mov_b32_e32 v6, v168
	v_mov_b32_e32 v7, v169
	v_mov_b32_e32 v8, v170
	v_mov_b32_e32 v9, v171
	v_mad_u64_u32 v[14:15], s[16:17], v28, s24, v[0:1]
	ds_read_b128 v[10:13], v14
	ds_read_b128 v[14:17], v14 offset:16
	v_lshl_add_u64 v[18:19], v[4:5], 0, v[20:21]
	v_lshlrev_b32_e32 v20, 16, v6
	v_and_b32_e32 v21, 0xffff0000, v6
	v_lshlrev_b32_e32 v6, 16, v7
	v_and_b32_e32 v7, 0xffff0000, v7
	v_lshlrev_b32_e32 v22, 16, v8
	v_and_b32_e32 v23, 0xffff0000, v8
	v_lshlrev_b32_e32 v8, 16, v9
	v_and_b32_e32 v9, 0xffff0000, v9
	s_waitcnt lgkmcnt(1)
	v_pk_mul_f32 v[10:11], v[10:11], v[20:21]
	v_pk_mul_f32 v[12:13], v[12:13], v[6:7]
	s_waitcnt lgkmcnt(0)
	v_pk_mul_f32 v[14:15], v[14:15], v[22:23]
	v_pk_mul_f32 v[16:17], v[16:17], v[8:9]
	v_cvt_pk_bf16_f32 v6, v10, v11
	v_cvt_pk_bf16_f32 v7, v12, v13
	v_cvt_pk_bf16_f32 v8, v14, v15
	v_cvt_pk_bf16_f32 v9, v16, v17
	global_store_dwordx4 v[18:19], v[6:9], off sc1
	s_add_i32 s25, s25, s65
	s_lshr_b32 s14, s25, 3
	s_and_b32 s16, s14, 0xffffff8
	s_cmpk_gt_u32 s25, 0x7f
	s_cselect_b64 s[14:15], -1, 0
	s_barrier
	s_branch .LBB0_395

; __device__ __forceinline__ int ltid() { int t = threadIdx.x; asm volatile("" : "+v"(t)); return t; }
; __device__ __forceinline__ void stage_acc(f32x16 (&acc)[2][2], float* sC) {
;   const int tid__ = ltid(); const int lane = tid__ & 63, wave = tid__ >> 6;
;   const int wm = wave >> 1, wn = wave & 1, l31 = lane & 31, hf = lane >> 5;
;   float* base = sC + (wm * 64 + 4 * hf) * 132 + wn * 64 + l31;
; #pragma unroll
;   for (int mi = 0; mi < 2; ++mi)
; #pragma unroll
;     for (int ni = 0; ni < 2; ++ni)
; #pragma unroll
;       for (int r = 0; r < 16; ++r) base[(mi * 32 + 8 * (r >> 2) + (r & 3)) * 132 + ni * 32] = acc[mi][ni][r];
;   __syncthreads();
; __device__ __forceinline__ void phase5(const Params& p, unsigned char* smem) {
;     ...
;     epilogue_rows(acc, m0, n0, smem, [&](int m, int n, float4 a, float4 b) {
;       uint4 g = *(const uint4*)(SGD + (size_t)m * 1024 + n);
;       uint4* ptr = (uint4*)(MERGED + (size_t)m * 1024 + n);
;       uint4 o = *ptr;
.LBB0_415:
	s_waitcnt vmcnt(7)
	v_mov_b32_e32 v64, v218
	s_mov_b32 s14, 0
	v_and_b32_e32 v65, 64, v64
	v_and_b32_e32 v66, 31, v64
	v_lshrrev_b32_e32 v67, 1, v64
	v_lshrrev_b32_e32 v64, 3, v64
	v_and_b32_e32 v64, 4, v64
	v_and_or_b32 v64, v67, s26, v64
	v_mul_lo_u32 v64, v64, s27
	v_add_u32_e32 v64, 16, v64
	v_lshlrev_b32_e32 v65, 2, v65
	v_lshlrev_b32_e32 v66, 2, v66
	v_add3_u32 v64, v64, v65, v66
	ds_write2_b32 v64, v48, v32 offset1:32
	ds_write2_b32 v64, v49, v33 offset0:132 offset1:164
	v_add_u32_e32 v32, 0x400, v64
	ds_write2_b32 v32, v50, v34 offset0:8 offset1:40
	ds_write2_b32 v32, v51, v35 offset0:140 offset1:172
	v_add_u32_e32 v32, 0x1000, v64
	ds_write2_b32 v32, v52, v36 offset0:32 offset1:64
	ds_write2_b32 v32, v53, v37 offset0:164 offset1:196
	v_add_u32_e32 v32, 0x1400, v64
	ds_write2_b32 v32, v54, v38 offset0:40 offset1:72
	ds_write2_b32 v32, v55, v39 offset0:172 offset1:204
	v_add_u32_e32 v32, 0x2000, v64
	ds_write2_b32 v32, v56, v40 offset0:64 offset1:96
	ds_write2_b32 v32, v57, v41 offset0:196 offset1:228
	v_add_u32_e32 v32, 0x2400, v64
	ds_write2_b32 v32, v58, v42 offset0:72 offset1:104
	ds_write2_b32 v32, v59, v43 offset0:204 offset1:236
	v_add_u32_e32 v32, 0x3000, v64
	ds_write2_b32 v32, v60, v44 offset0:96 offset1:128
	v_add_u32_e32 v32, 0x3200, v64
	ds_write2_b32 v32, v61, v45 offset0:100 offset1:132
	v_add_u32_e32 v32, 0x3400, v64
	ds_write2_b32 v32, v62, v46 offset0:104 offset1:136
	v_add_u32_e32 v32, 0x3600, v64
	ds_write2_b32 v32, v63, v47 offset0:108 offset1:140
	v_add_u32_e32 v32, 0x4000, v64
	ds_write2_b32 v32, v16, v0 offset0:128 offset1:160
	v_add_u32_e32 v0, 0x4400, v64
	ds_write2_b32 v0, v17, v1 offset0:4 offset1:36
	ds_write2_b32 v0, v18, v2 offset0:136 offset1:168
	v_add_u32_e32 v0, 0x4800, v64
	ds_write2_b32 v0, v19, v3 offset0:12 offset1:44
	v_add_u32_e32 v0, 0x5000, v64
	ds_write2_b32 v0, v20, v4 offset0:160 offset1:192
	v_add_u32_e32 v0, 0x5400, v64
	ds_write2_b32 v0, v21, v5 offset0:36 offset1:68
	ds_write2_b32 v0, v22, v6 offset0:168 offset1:200
	v_add_u32_e32 v0, 0x5800, v64
	ds_write2_b32 v0, v23, v7 offset0:44 offset1:76
	v_add_u32_e32 v0, 0x6000, v64
	ds_write2_b32 v0, v24, v8 offset0:192 offset1:224
	v_add_u32_e32 v0, 0x6400, v64
	ds_write2_b32 v0, v25, v9 offset0:68 offset1:100
	ds_write2_b32 v0, v26, v10 offset0:200 offset1:232
	v_add_u32_e32 v0, 0x6800, v64
	ds_write2_b32 v0, v27, v11 offset0:76 offset1:108
	v_add_u32_e32 v0, 0x7200, v64
	ds_write2_b32 v0, v28, v12 offset0:96 offset1:128
	v_add_u32_e32 v0, 0x7400, v64
	ds_write2_b32 v0, v29, v13 offset0:100 offset1:132
	v_add_u32_e32 v0, 0x7600, v64
	ds_write2_b32 v0, v30, v14 offset0:104 offset1:136
	v_add_u32_e32 v0, 0x7800, v64
	v_mov_b32_e32 v1, v218
	ds_write2_b32 v0, v31, v15 offset0:108 offset1:140
	v_lshlrev_b32_e32 v0, 3, v1
	v_and_b32_e32 v2, 0x78, v0
	v_or_b32_e32 v2, s30, v2
	v_ashrrev_i32_e32 v3, 31, v2
	v_lshlrev_b64 v[4:5], 1, v[2:3]
	v_lshl_add_u64 v[2:3], s[10:11], 0, v[4:5]
	v_lshl_add_u64 v[4:5], s[6:7], 0, v[4:5]
	s_movk_i32 s74, 0x0
	v_add_u32_e32 v16, s74, v1
	v_ashrrev_i32_e32 v17, 4, v16
	v_add_u32_e32 v6, s29, v17
	v_ashrrev_i32_e32 v7, 31, v6
	v_lshlrev_b64 v[6:7], 11, v[6:7]
	v_lshl_add_u64 v[22:23], v[4:5], 0, v[6:7]
	v_lshl_add_u64 v[14:15], v[2:3], 0, v[6:7]
	global_load_dwordx4 v[140:143], v[22:23], off
	global_load_dwordx4 v[144:147], v[14:15], off
	v_add_u32_e32 v14, 0x100, v16
	v_ashrrev_i32_e32 v36, 4, v14
	v_add_u32_e32 v24, s29, v36
	v_ashrrev_i32_e32 v25, 31, v24
	v_lshlrev_b64 v[24:25], 11, v[24:25]
	v_lshl_add_u64 v[26:27], v[2:3], 0, v[24:25]
	v_lshl_add_u64 v[24:25], v[4:5], 0, v[24:25]
	global_load_dwordx4 v[148:151], v[24:25], off
	global_load_dwordx4 v[152:155], v[26:27], off
	s_movk_i32 s74, 0x200
	v_add_u32_e32 v16, s74, v1
	v_ashrrev_i32_e32 v17, 4, v16
	v_add_u32_e32 v6, s29, v17
	v_ashrrev_i32_e32 v7, 31, v6
	v_lshlrev_b64 v[6:7], 11, v[6:7]
	v_lshl_add_u64 v[22:23], v[4:5], 0, v[6:7]
	v_lshl_add_u64 v[14:15], v[2:3], 0, v[6:7]
	global_load_dwordx4 v[156:159], v[22:23], off
	global_load_dwordx4 v[160:163], v[14:15], off
	v_add_u32_e32 v14, 0x100, v16
	v_ashrrev_i32_e32 v36, 4, v14
	v_add_u32_e32 v24, s29, v36
	v_ashrrev_i32_e32 v25, 31, v24
	v_lshlrev_b64 v[24:25], 11, v[24:25]
	v_lshl_add_u64 v[26:27], v[2:3], 0, v[24:25]
	v_lshl_add_u64 v[24:25], v[4:5], 0, v[24:25]
	global_load_dwordx4 v[164:167], v[24:25], off
	global_load_dwordx4 v[168:171], v[26:27], off
	s_movk_i32 s74, 0x400
	v_add_u32_e32 v16, s74, v1
	v_ashrrev_i32_e32 v17, 4, v16
	v_add_u32_e32 v6, s29, v17
	v_ashrrev_i32_e32 v7, 31, v6
	v_lshlrev_b64 v[6:7], 11, v[6:7]
	v_lshl_add_u64 v[22:23], v[4:5], 0, v[6:7]
	v_lshl_add_u64 v[14:15], v[2:3], 0, v[6:7]
	global_load_dwordx4 v[172:175], v[22:23], off
	global_load_dwordx4 v[176:179], v[14:15], off
	v_add_u32_e32 v14, 0x100, v16
	v_ashrrev_i32_e32 v36, 4, v14
	v_add_u32_e32 v24, s29, v36
	v_ashrrev_i32_e32 v25, 31, v24
	v_lshlrev_b64 v[24:25], 11, v[24:25]
	v_lshl_add_u64 v[26:27], v[2:3], 0, v[24:25]
	v_lshl_add_u64 v[24:25], v[4:5], 0, v[24:25]
	global_load_dwordx4 v[180:183], v[24:25], off
	global_load_dwordx4 v[184:187], v[26:27], off
	s_movk_i32 s74, 0x600
	v_add_u32_e32 v16, s74, v1
	v_ashrrev_i32_e32 v17, 4, v16
	v_add_u32_e32 v6, s29, v17
	v_ashrrev_i32_e32 v7, 31, v6
	v_lshlrev_b64 v[6:7], 11, v[6:7]
	v_lshl_add_u64 v[22:23], v[4:5], 0, v[6:7]
	v_lshl_add_u64 v[14:15], v[2:3], 0, v[6:7]
	global_load_dwordx4 v[188:191], v[22:23], off
	global_load_dwordx4 v[196:199], v[14:15], off
	v_add_u32_e32 v14, 0x100, v16
	v_ashrrev_i32_e32 v36, 4, v14
	v_add_u32_e32 v24, s29, v36
	v_ashrrev_i32_e32 v25, 31, v24
	v_lshlrev_b64 v[24:25], 11, v[24:25]
	v_lshl_add_u64 v[26:27], v[2:3], 0, v[24:25]
	v_lshl_add_u64 v[24:25], v[4:5], 0, v[24:25]
	global_load_dwordx4 v[200:203], v[24:25], off
	global_load_dwordx4 v[204:207], v[26:27], off
	s_waitcnt lgkmcnt(0)
	s_barrier
	s_nop 0
	v_lshlrev_b32_e32 v0, 3, v1
	v_and_b32_e32 v2, 0x78, v0
	v_lshl_add_u32 v0, v2, 2, 16
	v_or_b32_e32 v2, s30, v2
	v_ashrrev_i32_e32 v3, 31, v2
	v_lshlrev_b64 v[4:5], 1, v[2:3]
	v_lshl_add_u64 v[2:3], s[10:11], 0, v[4:5]
	v_lshl_add_u64 v[4:5], s[6:7], 0, v[4:5]
; __device__ __forceinline__ float bflo(unsigned v) { return __uint_as_float(v << 16); }
; __device__ __forceinline__ float bfhi(unsigned v) { return __uint_as_float(v & 0xffff0000u); }
; __device__ __forceinline__ uint4 pack8(float4 a, float4 b) { uint4 o; o.x = cvtpk(a.x, a.y); o.y = cvtpk(a.z, a.w); o.z = cvtpk(b.x, b.y); o.w = cvtpk(b.z, b.w); return o; }
; template <class Epi>
; __device__ __forceinline__ void epilogue_rows(f32x16 (&acc)[2][2], int m0, int n0, unsigned char* smem, Epi epi) {
;     ...
;   for (int it = 0; it < 8; ++it) {
;     int idx = tid + 256 * it; int r = idx >> 4, c8 = (idx & 15) * 8;
;     float4 a = *(const float4*)(sC + r * 132 + c8), b = *(const float4*)(sC + r * 132 + c8 + 4);
;     epi(m0 + r, n0 + c8, a, b);
;   }
; __device__ __forceinline__ void phase5(const Params& p, unsigned char* smem) {
;     ...
;     epilogue_rows(acc, m0, n0, smem, [&](int m, int n, float4 a, float4 b) {
;       uint4 g = *(const uint4*)(SGD + (size_t)m * 1024 + n);
;       uint4* ptr = (uint4*)(MERGED + (size_t)m * 1024 + n);
;       uint4 o = *ptr;
;       a.x = bflo(o.x) + a.x * bflo(g.x); a.y = bfhi(o.x) + a.y * bfhi(g.x); a.z = bflo(o.y) + a.z * bflo(g.y); a.w = bfhi(o.y) + a.w * bfhi(g.y);
;       b.x = bflo(o.z) + b.x * bflo(g.z); b.y = bfhi(o.z) + b.y * bfhi(g.z); b.z = bflo(o.w) + b.z * bflo(g.w); b.w = bfhi(o.w) + b.w * bfhi(g.w);
;       *ptr = pack8(a, b);
;     });
.LBB0_416:
	s_waitcnt vmcnt(0)
	v_add_u32_e32 v16, s14, v1
	v_ashrrev_i32_e32 v17, 4, v16
	v_add_u32_e32 v6, s29, v17
	v_ashrrev_i32_e32 v7, 31, v6
	v_lshlrev_b64 v[6:7], 11, v[6:7]
	v_lshl_add_u64 v[22:23], v[4:5], 0, v[6:7]
	v_lshl_add_u64 v[14:15], v[2:3], 0, v[6:7]
	v_mov_b32_e32 v6, v140
	v_mov_b32_e32 v7, v141
	v_mov_b32_e32 v8, v142
	v_mov_b32_e32 v9, v143
	v_mov_b32_e32 v10, v144
	v_mov_b32_e32 v11, v145
	v_mov_b32_e32 v12, v146
	v_mov_b32_e32 v13, v147
	v_add_u32_e32 v14, 0x100, v16
	v_mad_u64_u32 v[18:19], s[16:17], v17, s27, v[0:1]
	v_ashrrev_i32_e32 v36, 4, v14
	ds_read_b128 v[14:17], v18
	ds_read_b128 v[18:21], v18 offset:16
	v_add_u32_e32 v24, s29, v36
	v_ashrrev_i32_e32 v25, 31, v24
	v_lshlrev_b64 v[24:25], 11, v[24:25]
	v_lshl_add_u64 v[26:27], v[2:3], 0, v[24:25]
	v_lshl_add_u64 v[24:25], v[4:5], 0, v[24:25]
	s_addk_i32 s14, 0x200
	s_cmpk_lg_i32 s14, 0x800
	v_lshlrev_b32_e32 v28, 16, v6
	v_lshlrev_b32_e32 v30, 16, v10
	v_and_b32_e32 v29, 0xffff0000, v6
	v_and_b32_e32 v31, 0xffff0000, v10
	v_lshlrev_b32_e32 v6, 16, v7
	v_lshlrev_b32_e32 v10, 16, v11
	v_and_b32_e32 v7, 0xffff0000, v7
	v_and_b32_e32 v11, 0xffff0000, v11
	v_lshlrev_b32_e32 v32, 16, v8
	v_lshlrev_b32_e32 v34, 16, v12
	v_and_b32_e32 v33, 0xffff0000, v8
	v_and_b32_e32 v35, 0xffff0000, v12
	v_lshlrev_b32_e32 v8, 16, v9
	v_lshlrev_b32_e32 v12, 16, v13
	v_and_b32_e32 v9, 0xffff0000, v9
	v_and_b32_e32 v13, 0xffff0000, v13
	s_waitcnt lgkmcnt(1)
	v_pk_fma_f32 v[14:15], v[14:15], v[30:31], v[28:29]
	v_pk_fma_f32 v[10:11], v[16:17], v[10:11], v[6:7]
	s_waitcnt lgkmcnt(0)
	v_pk_fma_f32 v[16:17], v[18:19], v[34:35], v[32:33]
	v_pk_fma_f32 v[12:13], v[20:21], v[12:13], v[8:9]
	v_cvt_pk_bf16_f32 v6, v14, v15
	v_cvt_pk_bf16_f32 v7, v10, v11
	v_cvt_pk_bf16_f32 v8, v16, v17
	v_cvt_pk_bf16_f32 v9, v12, v13
	global_store_dwordx4 v[22:23], v[6:9], off sc1
	s_nop 1
	v_mov_b32_e32 v6, v148
	v_mov_b32_e32 v7, v149
	v_mov_b32_e32 v8, v150
	v_mov_b32_e32 v9, v151
	s_nop 0
	v_mov_b32_e32 v10, v152
	v_mov_b32_e32 v11, v153
	v_mov_b32_e32 v12, v154
	v_mov_b32_e32 v13, v155
	v_mad_u64_u32 v[18:19], s[16:17], v36, s27, v[0:1]
	ds_read_b128 v[14:17], v18
	ds_read_b128 v[18:21], v18 offset:16
	v_lshlrev_b32_e32 v22, 16, v6
	v_lshlrev_b32_e32 v26, 16, v10
	v_and_b32_e32 v23, 0xffff0000, v6
	v_and_b32_e32 v27, 0xffff0000, v10
	v_lshlrev_b32_e32 v6, 16, v7
	v_lshlrev_b32_e32 v10, 16, v11
	v_and_b32_e32 v7, 0xffff0000, v7
	v_and_b32_e32 v11, 0xffff0000, v11
	v_lshlrev_b32_e32 v28, 16, v8
	v_lshlrev_b32_e32 v30, 16, v12
	v_and_b32_e32 v29, 0xffff0000, v8
	v_and_b32_e32 v31, 0xffff0000, v12
	v_lshlrev_b32_e32 v8, 16, v9
	v_lshlrev_b32_e32 v12, 16, v13
	v_and_b32_e32 v9, 0xffff0000, v9
	v_and_b32_e32 v13, 0xffff0000, v13
	s_waitcnt lgkmcnt(1)
	v_pk_fma_f32 v[14:15], v[14:15], v[26:27], v[22:23]
	v_pk_fma_f32 v[10:11], v[16:17], v[10:11], v[6:7]
	s_waitcnt lgkmcnt(0)
	v_pk_fma_f32 v[16:17], v[18:19], v[30:31], v[28:29]
	v_pk_fma_f32 v[12:13], v[20:21], v[12:13], v[8:9]
	v_cvt_pk_bf16_f32 v6, v14, v15
	v_cvt_pk_bf16_f32 v7, v10, v11
	v_cvt_pk_bf16_f32 v8, v16, v17
	v_cvt_pk_bf16_f32 v9, v12, v13
	global_store_dwordx4 v[24:25], v[6:9], off sc1
	v_add_u32_e32 v16, s14, v1
	v_ashrrev_i32_e32 v17, 4, v16
	v_add_u32_e32 v6, s29, v17
	v_ashrrev_i32_e32 v7, 31, v6
	v_lshlrev_b64 v[6:7], 11, v[6:7]
	v_lshl_add_u64 v[22:23], v[4:5], 0, v[6:7]
	v_lshl_add_u64 v[14:15], v[2:3], 0, v[6:7]
	v_mov_b32_e32 v6, v156
	v_mov_b32_e32 v7, v157
	v_mov_b32_e32 v8, v158
	v_mov_b32_e32 v9, v159
	v_mov_b32_e32 v10, v160
	v_mov_b32_e32 v11, v161
	v_mov_b32_e32 v12, v162
	v_mov_b32_e32 v13, v163
	v_add_u32_e32 v14, 0x100, v16
	v_mad_u64_u32 v[18:19], s[16:17], v17, s27, v[0:1]
	v_ashrrev_i32_e32 v36, 4, v14
	ds_read_b128 v[14:17], v18
	ds_read_b128 v[18:21], v18 offset:16
	v_add_u32_e32 v24, s29, v36
	v_ashrrev_i32_e32 v25, 31, v24
	v_lshlrev_b64 v[24:25], 11, v[24:25]
	v_lshl_add_u64 v[26:27], v[2:3], 0, v[24:25]
	v_lshl_add_u64 v[24:25], v[4:5], 0, v[24:25]
	s_addk_i32 s14, 0x200
	s_cmpk_lg_i32 s14, 0x800
	v_lshlrev_b32_e32 v28, 16, v6
	v_lshlrev_b32_e32 v30, 16, v10
	v_and_b32_e32 v29, 0xffff0000, v6
	v_and_b32_e32 v31, 0xffff0000, v10
	v_lshlrev_b32_e32 v6, 16, v7
	v_lshlrev_b32_e32 v10, 16, v11
	v_and_b32_e32 v7, 0xffff0000, v7
	v_and_b32_e32 v11, 0xffff0000, v11
	v_lshlrev_b32_e32 v32, 16, v8
	v_lshlrev_b32_e32 v34, 16, v12
	v_and_b32_e32 v33, 0xffff0000, v8
	v_and_b32_e32 v35, 0xffff0000, v12
	v_lshlrev_b32_e32 v8, 16, v9
	v_lshlrev_b32_e32 v12, 16, v13
	v_and_b32_e32 v9, 0xffff0000, v9
	v_and_b32_e32 v13, 0xffff0000, v13
	s_waitcnt lgkmcnt(1)
	v_pk_fma_f32 v[14:15], v[14:15], v[30:31], v[28:29]
	v_pk_fma_f32 v[10:11], v[16:17], v[10:11], v[6:7]
	s_waitcnt lgkmcnt(0)
	v_pk_fma_f32 v[16:17], v[18:19], v[34:35], v[32:33]
	v_pk_fma_f32 v[12:13], v[20:21], v[12:13], v[8:9]
	v_cvt_pk_bf16_f32 v6, v14, v15
	v_cvt_pk_bf16_f32 v7, v10, v11
	v_cvt_pk_bf16_f32 v8, v16, v17
	v_cvt_pk_bf16_f32 v9, v12, v13
	global_store_dwordx4 v[22:23], v[6:9], off sc1
	s_nop 1
	v_mov_b32_e32 v6, v164
	v_mov_b32_e32 v7, v165
	v_mov_b32_e32 v8, v166
	v_mov_b32_e32 v9, v167
	s_nop 0
	v_mov_b32_e32 v10, v168
	v_mov_b32_e32 v11, v169
	v_mov_b32_e32 v12, v170
	v_mov_b32_e32 v13, v171
	v_mad_u64_u32 v[18:19], s[16:17], v36, s27, v[0:1]
	ds_read_b128 v[14:17], v18
	ds_read_b128 v[18:21], v18 offset:16
	v_lshlrev_b32_e32 v22, 16, v6
	v_lshlrev_b32_e32 v26, 16, v10
	v_and_b32_e32 v23, 0xffff0000, v6
	v_and_b32_e32 v27, 0xffff0000, v10
	v_lshlrev_b32_e32 v6, 16, v7
	v_lshlrev_b32_e32 v10, 16, v11
	v_and_b32_e32 v7, 0xffff0000, v7
	v_and_b32_e32 v11, 0xffff0000, v11
	v_lshlrev_b32_e32 v28, 16, v8
	v_lshlrev_b32_e32 v30, 16, v12
	v_and_b32_e32 v29, 0xffff0000, v8
	v_and_b32_e32 v31, 0xffff0000, v12
	v_lshlrev_b32_e32 v8, 16, v9
	v_lshlrev_b32_e32 v12, 16, v13
	v_and_b32_e32 v9, 0xffff0000, v9
	v_and_b32_e32 v13, 0xffff0000, v13
	s_waitcnt lgkmcnt(1)
; __device__ __forceinline__ float bflo(unsigned v) { return __uint_as_float(v << 16); }
; __device__ __forceinline__ float bfhi(unsigned v) { return __uint_as_float(v & 0xffff0000u); }
; __device__ __forceinline__ uint4 pack8(float4 a, float4 b) { uint4 o; o.x = cvtpk(a.x, a.y); o.y = cvtpk(a.z, a.w); o.z = cvtpk(b.x, b.y); o.w = cvtpk(b.z, b.w); return o; }
; template <class Epi>
; __device__ __forceinline__ void epilogue_rows(f32x16 (&acc)[2][2], int m0, int n0, unsigned char* smem, Epi epi) {
;     ...
;   for (int it = 0; it < 8; ++it) {
;     int idx = tid + 256 * it; int r = idx >> 4, c8 = (idx & 15) * 8;
;     float4 a = *(const float4*)(sC + r * 132 + c8), b = *(const float4*)(sC + r * 132 + c8 + 4);
;     epi(m0 + r, n0 + c8, a, b);
;   }
; __device__ __forceinline__ void phase5(const Params& p, unsigned char* smem) {
;     ...
;     epilogue_rows(acc, m0, n0, smem, [&](int m, int n, float4 a, float4 b) {
;       uint4 g = *(const uint4*)(SGD + (size_t)m * 1024 + n);
;       uint4* ptr = (uint4*)(MERGED + (size_t)m * 1024 + n);
;       uint4 o = *ptr;
;       a.x = bflo(o.x) + a.x * bflo(g.x); a.y = bfhi(o.x) + a.y * bfhi(g.x); a.z = bflo(o.y) + a.z * bflo(g.y); a.w = bfhi(o.y) + a.w * bfhi(g.y);
;       b.x = bflo(o.z) + b.x * bflo(g.z); b.y = bfhi(o.z) + b.y * bfhi(g.z); b.z = bflo(o.w) + b.z * bflo(g.w); b.w = bfhi(o.w) + b.w * bfhi(g.w);
;       *ptr = pack8(a, b);
;     });
	v_pk_fma_f32 v[14:15], v[14:15], v[26:27], v[22:23]
	v_pk_fma_f32 v[10:11], v[16:17], v[10:11], v[6:7]
	s_waitcnt lgkmcnt(0)
	v_pk_fma_f32 v[16:17], v[18:19], v[30:31], v[28:29]
	v_pk_fma_f32 v[12:13], v[20:21], v[12:13], v[8:9]
	v_cvt_pk_bf16_f32 v6, v14, v15
	v_cvt_pk_bf16_f32 v7, v10, v11
	v_cvt_pk_bf16_f32 v8, v16, v17
	v_cvt_pk_bf16_f32 v9, v12, v13
	global_store_dwordx4 v[24:25], v[6:9], off sc1
	v_add_u32_e32 v16, s14, v1
	v_ashrrev_i32_e32 v17, 4, v16
	v_add_u32_e32 v6, s29, v17
	v_ashrrev_i32_e32 v7, 31, v6
	v_lshlrev_b64 v[6:7], 11, v[6:7]
	v_lshl_add_u64 v[22:23], v[4:5], 0, v[6:7]
	v_lshl_add_u64 v[14:15], v[2:3], 0, v[6:7]
	v_mov_b32_e32 v6, v172
	v_mov_b32_e32 v7, v173
	v_mov_b32_e32 v8, v174
	v_mov_b32_e32 v9, v175
	v_mov_b32_e32 v10, v176
	v_mov_b32_e32 v11, v177
	v_mov_b32_e32 v12, v178
	v_mov_b32_e32 v13, v179
	v_add_u32_e32 v14, 0x100, v16
	v_mad_u64_u32 v[18:19], s[16:17], v17, s27, v[0:1]
	v_ashrrev_i32_e32 v36, 4, v14
	ds_read_b128 v[14:17], v18
	ds_read_b128 v[18:21], v18 offset:16
	v_add_u32_e32 v24, s29, v36
	v_ashrrev_i32_e32 v25, 31, v24
	v_lshlrev_b64 v[24:25], 11, v[24:25]
	v_lshl_add_u64 v[26:27], v[2:3], 0, v[24:25]
	v_lshl_add_u64 v[24:25], v[4:5], 0, v[24:25]
	s_addk_i32 s14, 0x200
	s_cmpk_lg_i32 s14, 0x800
	v_lshlrev_b32_e32 v28, 16, v6
	v_lshlrev_b32_e32 v30, 16, v10
	v_and_b32_e32 v29, 0xffff0000, v6
	v_and_b32_e32 v31, 0xffff0000, v10
	v_lshlrev_b32_e32 v6, 16, v7
	v_lshlrev_b32_e32 v10, 16, v11
	v_and_b32_e32 v7, 0xffff0000, v7
	v_and_b32_e32 v11, 0xffff0000, v11
	v_lshlrev_b32_e32 v32, 16, v8
	v_lshlrev_b32_e32 v34, 16, v12
	v_and_b32_e32 v33, 0xffff0000, v8
	v_and_b32_e32 v35, 0xffff0000, v12
	v_lshlrev_b32_e32 v8, 16, v9
	v_lshlrev_b32_e32 v12, 16, v13
	v_and_b32_e32 v9, 0xffff0000, v9
	v_and_b32_e32 v13, 0xffff0000, v13
	s_waitcnt lgkmcnt(1)
	v_pk_fma_f32 v[14:15], v[14:15], v[30:31], v[28:29]
	v_pk_fma_f32 v[10:11], v[16:17], v[10:11], v[6:7]
	s_waitcnt lgkmcnt(0)
	v_pk_fma_f32 v[16:17], v[18:19], v[34:35], v[32:33]
	v_pk_fma_f32 v[12:13], v[20:21], v[12:13], v[8:9]
	v_cvt_pk_bf16_f32 v6, v14, v15
	v_cvt_pk_bf16_f32 v7, v10, v11
	v_cvt_pk_bf16_f32 v8, v16, v17
	v_cvt_pk_bf16_f32 v9, v12, v13
	global_store_dwordx4 v[22:23], v[6:9], off sc1
	s_nop 1
	v_mov_b32_e32 v6, v180
	v_mov_b32_e32 v7, v181
	v_mov_b32_e32 v8, v182
	v_mov_b32_e32 v9, v183
	s_nop 0
	v_mov_b32_e32 v10, v184
	v_mov_b32_e32 v11, v185
	v_mov_b32_e32 v12, v186
	v_mov_b32_e32 v13, v187
	v_mad_u64_u32 v[18:19], s[16:17], v36, s27, v[0:1]
	ds_read_b128 v[14:17], v18
	ds_read_b128 v[18:21], v18 offset:16
	v_lshlrev_b32_e32 v22, 16, v6
	v_lshlrev_b32_e32 v26, 16, v10
	v_and_b32_e32 v23, 0xffff0000, v6
	v_and_b32_e32 v27, 0xffff0000, v10
	v_lshlrev_b32_e32 v6, 16, v7
	v_lshlrev_b32_e32 v10, 16, v11
	v_and_b32_e32 v7, 0xffff0000, v7
	v_and_b32_e32 v11, 0xffff0000, v11
	v_lshlrev_b32_e32 v28, 16, v8
	v_lshlrev_b32_e32 v30, 16, v12
	v_and_b32_e32 v29, 0xffff0000, v8
	v_and_b32_e32 v31, 0xffff0000, v12
	v_lshlrev_b32_e32 v8, 16, v9
	v_lshlrev_b32_e32 v12, 16, v13
	v_and_b32_e32 v9, 0xffff0000, v9
	v_and_b32_e32 v13, 0xffff0000, v13
	s_waitcnt lgkmcnt(1)
	v_pk_fma_f32 v[14:15], v[14:15], v[26:27], v[22:23]
	v_pk_fma_f32 v[10:11], v[16:17], v[10:11], v[6:7]
	s_waitcnt lgkmcnt(0)
	v_pk_fma_f32 v[16:17], v[18:19], v[30:31], v[28:29]
	v_pk_fma_f32 v[12:13], v[20:21], v[12:13], v[8:9]
	v_cvt_pk_bf16_f32 v6, v14, v15
	v_cvt_pk_bf16_f32 v7, v10, v11
	v_cvt_pk_bf16_f32 v8, v16, v17
	v_cvt_pk_bf16_f32 v9, v12, v13
	global_store_dwordx4 v[24:25], v[6:9], off sc1
	v_add_u32_e32 v16, s14, v1
	v_ashrrev_i32_e32 v17, 4, v16
	v_add_u32_e32 v6, s29, v17
	v_ashrrev_i32_e32 v7, 31, v6
	v_lshlrev_b64 v[6:7], 11, v[6:7]
	v_lshl_add_u64 v[22:23], v[4:5], 0, v[6:7]
	v_lshl_add_u64 v[14:15], v[2:3], 0, v[6:7]
	v_mov_b32_e32 v6, v188
	v_mov_b32_e32 v7, v189
	v_mov_b32_e32 v8, v190
	v_mov_b32_e32 v9, v191
	v_mov_b32_e32 v10, v196
	v_mov_b32_e32 v11, v197
	v_mov_b32_e32 v12, v198
	v_mov_b32_e32 v13, v199
	v_add_u32_e32 v14, 0x100, v16
	v_mad_u64_u32 v[18:19], s[16:17], v17, s27, v[0:1]
	v_ashrrev_i32_e32 v36, 4, v14
	ds_read_b128 v[14:17], v18
	ds_read_b128 v[18:21], v18 offset:16
	v_add_u32_e32 v24, s29, v36
	v_ashrrev_i32_e32 v25, 31, v24
	v_lshlrev_b64 v[24:25], 11, v[24:25]
	v_lshl_add_u64 v[26:27], v[2:3], 0, v[24:25]
	v_lshl_add_u64 v[24:25], v[4:5], 0, v[24:25]
	s_addk_i32 s14, 0x200
	s_cmpk_lg_i32 s14, 0x800
	v_lshlrev_b32_e32 v28, 16, v6
	v_lshlrev_b32_e32 v30, 16, v10
	v_and_b32_e32 v29, 0xffff0000, v6
	v_and_b32_e32 v31, 0xffff0000, v10
	v_lshlrev_b32_e32 v6, 16, v7
	v_lshlrev_b32_e32 v10, 16, v11
	v_and_b32_e32 v7, 0xffff0000, v7
	v_and_b32_e32 v11, 0xffff0000, v11
	v_lshlrev_b32_e32 v32, 16, v8
	v_lshlrev_b32_e32 v34, 16, v12
	v_and_b32_e32 v33, 0xffff0000, v8
	v_and_b32_e32 v35, 0xffff0000, v12
	v_lshlrev_b32_e32 v8, 16, v9
	v_lshlrev_b32_e32 v12, 16, v13
	v_and_b32_e32 v9, 0xffff0000, v9
	v_and_b32_e32 v13, 0xffff0000, v13
	s_waitcnt lgkmcnt(1)
	v_pk_fma_f32 v[14:15], v[14:15], v[30:31], v[28:29]
	v_pk_fma_f32 v[10:11], v[16:17], v[10:11], v[6:7]
	s_waitcnt lgkmcnt(0)
	v_pk_fma_f32 v[16:17], v[18:19], v[34:35], v[32:33]
	v_pk_fma_f32 v[12:13], v[20:21], v[12:13], v[8:9]
	v_cvt_pk_bf16_f32 v6, v14, v15
	v_cvt_pk_bf16_f32 v7, v10, v11
	v_cvt_pk_bf16_f32 v8, v16, v17
	v_cvt_pk_bf16_f32 v9, v12, v13
	global_store_dwordx4 v[22:23], v[6:9], off sc1
	s_nop 1
	v_mov_b32_e32 v6, v200
	v_mov_b32_e32 v7, v201
	v_mov_b32_e32 v8, v202
	v_mov_b32_e32 v9, v203
	s_nop 0
	v_mov_b32_e32 v10, v204
	v_mov_b32_e32 v11, v205
	v_mov_b32_e32 v12, v206
	v_mov_b32_e32 v13, v207
	v_mad_u64_u32 v[18:19], s[16:17], v36, s27, v[0:1]
	ds_read_b128 v[14:17], v18
	ds_read_b128 v[18:21], v18 offset:16
	v_lshlrev_b32_e32 v22, 16, v6
	v_lshlrev_b32_e32 v26, 16, v10
	v_and_b32_e32 v23, 0xffff0000, v6
	v_and_b32_e32 v27, 0xffff0000, v10
	v_lshlrev_b32_e32 v6, 16, v7
	v_lshlrev_b32_e32 v10, 16, v11
	v_and_b32_e32 v7, 0xffff0000, v7
	v_and_b32_e32 v11, 0xffff0000, v11
	v_lshlrev_b32_e32 v28, 16, v8
	v_lshlrev_b32_e32 v30, 16, v12
	v_and_b32_e32 v29, 0xffff0000, v8
	v_and_b32_e32 v31, 0xffff0000, v12
	v_lshlrev_b32_e32 v8, 16, v9
	v_lshlrev_b32_e32 v12, 16, v13
	v_and_b32_e32 v9, 0xffff0000, v9
	v_and_b32_e32 v13, 0xffff0000, v13
	s_waitcnt lgkmcnt(1)
	v_pk_fma_f32 v[14:15], v[14:15], v[26:27], v[22:23]
	v_pk_fma_f32 v[10:11], v[16:17], v[10:11], v[6:7]
	s_waitcnt lgkmcnt(0)
	v_pk_fma_f32 v[16:17], v[18:19], v[30:31], v[28:29]
	v_pk_fma_f32 v[12:13], v[20:21], v[12:13], v[8:9]
	v_cvt_pk_bf16_f32 v6, v14, v15
	v_cvt_pk_bf16_f32 v7, v10, v11
	v_cvt_pk_bf16_f32 v8, v16, v17
	v_cvt_pk_bf16_f32 v9, v12, v13
	global_store_dwordx4 v[24:25], v[6:9], off sc1
	s_add_i32 s28, s28, s65
	s_lshr_b32 s14, s28, 3
	s_and_b32 s18, s14, 0x7fffff8
	s_cmpk_gt_u32 s28, 0x7f
	s_cselect_b64 s[16:17], -1, 0
	s_barrier
	s_branch .LBB0_407

; __device__ __forceinline__ int ltid() { int t = threadIdx.x; asm volatile("" : "+v"(t)); return t; }
; __device__ __forceinline__ void stage_acc(f32x16 (&acc)[2][2], float* sC) {
;   const int tid__ = ltid(); const int lane = tid__ & 63, wave = tid__ >> 6;
;   const int wm = wave >> 1, wn = wave & 1, l31 = lane & 31, hf = lane >> 5;
;   float* base = sC + (wm * 64 + 4 * hf) * 132 + wn * 64 + l31;
; #pragma unroll
;   for (int mi = 0; mi < 2; ++mi)
; #pragma unroll
;     for (int ni = 0; ni < 2; ++ni)
; #pragma unroll
;       for (int r = 0; r < 16; ++r) base[(mi * 32 + 8 * (r >> 2) + (r & 3)) * 132 + ni * 32] = acc[mi][ni][r];
;   __syncthreads();
; __device__ __forceinline__ void phase6(const Params& p, unsigned char* smem) {
;     ...
;     epilogue_rows(acc, m0, n0, smem, [&](int m, int n, float4 a, float4 b) {
;       const float4* xp = (const float4*)(p.x + (size_t)m * 1024 + n);
;       float4 x0 = xp[0], x1 = xp[1];
.LBB0_435:
	s_waitcnt vmcnt(7)
	v_mov_b32_e32 v64, v218
	s_mov_b32 s24, 0
	v_and_b32_e32 v65, 64, v64
	v_and_b32_e32 v66, 31, v64
	v_lshrrev_b32_e32 v67, 1, v64
	v_lshrrev_b32_e32 v64, 3, v64
	v_and_b32_e32 v64, 4, v64
	v_and_or_b32 v64, v67, s34, v64
	v_mul_lo_u32 v64, v64, s35
	v_add_u32_e32 v64, 16, v64
	v_lshlrev_b32_e32 v65, 2, v65
	v_lshlrev_b32_e32 v66, 2, v66
	v_add3_u32 v64, v64, v65, v66
	ds_write2_b32 v64, v48, v32 offset1:32
	ds_write2_b32 v64, v49, v33 offset0:132 offset1:164
	v_add_u32_e32 v32, 0x400, v64
	ds_write2_b32 v32, v50, v34 offset0:8 offset1:40
	ds_write2_b32 v32, v51, v35 offset0:140 offset1:172
	v_add_u32_e32 v32, 0x1000, v64
	ds_write2_b32 v32, v52, v36 offset0:32 offset1:64
	ds_write2_b32 v32, v53, v37 offset0:164 offset1:196
	v_add_u32_e32 v32, 0x1400, v64
	ds_write2_b32 v32, v54, v38 offset0:40 offset1:72
	ds_write2_b32 v32, v55, v39 offset0:172 offset1:204
	v_add_u32_e32 v32, 0x2000, v64
	ds_write2_b32 v32, v56, v40 offset0:64 offset1:96
	ds_write2_b32 v32, v57, v41 offset0:196 offset1:228
	v_add_u32_e32 v32, 0x2400, v64
	ds_write2_b32 v32, v58, v42 offset0:72 offset1:104
	ds_write2_b32 v32, v59, v43 offset0:204 offset1:236
	v_add_u32_e32 v32, 0x3000, v64
	ds_write2_b32 v32, v60, v44 offset0:96 offset1:128
	v_add_u32_e32 v32, 0x3200, v64
	ds_write2_b32 v32, v61, v45 offset0:100 offset1:132
	v_add_u32_e32 v32, 0x3400, v64
	ds_write2_b32 v32, v62, v46 offset0:104 offset1:136
	v_add_u32_e32 v32, 0x3600, v64
	ds_write2_b32 v32, v63, v47 offset0:108 offset1:140
	v_add_u32_e32 v32, 0x4000, v64
	ds_write2_b32 v32, v16, v0 offset0:128 offset1:160
	v_add_u32_e32 v0, 0x4400, v64
	ds_write2_b32 v0, v17, v1 offset0:4 offset1:36
	ds_write2_b32 v0, v18, v2 offset0:136 offset1:168
	v_add_u32_e32 v0, 0x4800, v64
	ds_write2_b32 v0, v19, v3 offset0:12 offset1:44
	v_add_u32_e32 v0, 0x5000, v64
	ds_write2_b32 v0, v20, v4 offset0:160 offset1:192
	v_add_u32_e32 v0, 0x5400, v64
	ds_write2_b32 v0, v21, v5 offset0:36 offset1:68
	ds_write2_b32 v0, v22, v6 offset0:168 offset1:200
	v_add_u32_e32 v0, 0x5800, v64
	v_xor_b32_e32 v4, 1, v194
	ds_write2_b32 v0, v23, v7 offset0:44 offset1:76
	v_add_u32_e32 v0, 0x6000, v64
	v_cmp_lt_i32_e32 vcc, v4, v195
	ds_write2_b32 v0, v24, v8 offset0:192 offset1:224
	v_add_u32_e32 v0, 0x6400, v64
	v_cndmask_b32_e32 v4, v194, v4, vcc
	ds_write2_b32 v0, v25, v9 offset0:68 offset1:100
	ds_write2_b32 v0, v26, v10 offset0:200 offset1:232
	v_add_u32_e32 v0, 0x6800, v64
	v_lshlrev_b32_e32 v8, 2, v4
	v_xor_b32_e32 v4, 2, v194
	ds_write2_b32 v0, v27, v11 offset0:76 offset1:108
	v_add_u32_e32 v0, 0x7200, v64
	v_cmp_lt_i32_e32 vcc, v4, v195
	ds_write2_b32 v0, v28, v12 offset0:96 offset1:128
	v_add_u32_e32 v0, 0x7400, v64
	v_cndmask_b32_e32 v4, v194, v4, vcc
	ds_write2_b32 v0, v29, v13 offset0:100 offset1:132
	v_add_u32_e32 v0, 0x7600, v64
	v_lshlrev_b32_e32 v9, 2, v4
	v_xor_b32_e32 v4, 4, v194
	ds_write2_b32 v0, v30, v14 offset0:104 offset1:136
	v_add_u32_e32 v0, 0x7800, v64
	v_mov_b32_e32 v1, v218
	v_cmp_lt_i32_e32 vcc, v4, v195
	ds_write2_b32 v0, v31, v15 offset0:108 offset1:140
	v_lshlrev_b32_e32 v0, 3, v1
	v_and_b32_e32 v2, 0x78, v0
	v_or_b32_e32 v2, s21, v2
	v_ashrrev_i32_e32 v3, 31, v2
	v_lshlrev_b64 v[212:213], 2, v[2:3]
	v_lshl_add_u64 v[2:3], s[8:9], 0, v[212:213]
	s_movk_i32 s74, 0x0
	v_add_u32_e32 v12, s74, v1
	v_ashrrev_i32_e32 v13, 4, v12
	v_add_u32_e32 v6, s38, v13
	v_ashrrev_i32_e32 v7, 31, v6
	v_lshlrev_b64 v[30:31], 12, v[6:7]
	v_lshl_add_u64 v[22:23], v[2:3], 0, v[30:31]
	global_load_dwordx4 v[144:147], v[22:23], off
	global_load_dwordx4 v[148:151], v[22:23], off offset:16
	v_add_u32_e32 v6, 0x100, v12
	v_ashrrev_i32_e32 v22, 4, v6
	v_add_u32_e32 v6, s38, v22
	v_ashrrev_i32_e32 v7, 31, v6
	v_lshlrev_b64 v[28:29], 12, v[6:7]
	v_lshl_add_u64 v[20:21], v[2:3], 0, v[28:29]
	global_load_dwordx4 v[152:155], v[20:21], off
	global_load_dwordx4 v[156:159], v[20:21], off offset:16
	s_movk_i32 s74, 0x200
	v_add_u32_e32 v12, s74, v1
	v_ashrrev_i32_e32 v13, 4, v12
	v_add_u32_e32 v6, s38, v13
	v_ashrrev_i32_e32 v7, 31, v6
	v_lshlrev_b64 v[30:31], 12, v[6:7]
	v_lshl_add_u64 v[22:23], v[2:3], 0, v[30:31]
	global_load_dwordx4 v[160:163], v[22:23], off
	global_load_dwordx4 v[164:167], v[22:23], off offset:16
	v_add_u32_e32 v6, 0x100, v12
	v_ashrrev_i32_e32 v22, 4, v6
	v_add_u32_e32 v6, s38, v22
	v_ashrrev_i32_e32 v7, 31, v6
	v_lshlrev_b64 v[28:29], 12, v[6:7]
	v_lshl_add_u64 v[20:21], v[2:3], 0, v[28:29]
	global_load_dwordx4 v[168:171], v[20:21], off
	global_load_dwordx4 v[172:175], v[20:21], off offset:16
	s_movk_i32 s74, 0x400
	v_add_u32_e32 v12, s74, v1
	v_ashrrev_i32_e32 v13, 4, v12
	v_add_u32_e32 v6, s38, v13
	v_ashrrev_i32_e32 v7, 31, v6
	v_lshlrev_b64 v[30:31], 12, v[6:7]
	v_lshl_add_u64 v[22:23], v[2:3], 0, v[30:31]
	global_load_dwordx4 v[176:179], v[22:23], off
	global_load_dwordx4 v[180:183], v[22:23], off offset:16
	v_add_u32_e32 v6, 0x100, v12
	v_ashrrev_i32_e32 v22, 4, v6
	v_add_u32_e32 v6, s38, v22
	v_ashrrev_i32_e32 v7, 31, v6
	v_lshlrev_b64 v[28:29], 12, v[6:7]
	v_lshl_add_u64 v[20:21], v[2:3], 0, v[28:29]
	global_load_dwordx4 v[184:187], v[20:21], off
	global_load_dwordx4 v[188:191], v[20:21], off offset:16
	s_movk_i32 s74, 0x600
	v_add_u32_e32 v12, s74, v1
	v_ashrrev_i32_e32 v13, 4, v12
	v_add_u32_e32 v6, s38, v13
	v_ashrrev_i32_e32 v7, 31, v6
	v_lshlrev_b64 v[30:31], 12, v[6:7]
	v_lshl_add_u64 v[22:23], v[2:3], 0, v[30:31]
	global_load_dwordx4 v[196:199], v[22:23], off
	global_load_dwordx4 v[200:203], v[22:23], off offset:16
	v_add_u32_e32 v6, 0x100, v12
	v_ashrrev_i32_e32 v22, 4, v6
	v_add_u32_e32 v6, s38, v22
	v_ashrrev_i32_e32 v7, 31, v6
	v_lshlrev_b64 v[28:29], 12, v[6:7]
	v_lshl_add_u64 v[20:21], v[2:3], 0, v[28:29]
	global_load_dwordx4 v[204:207], v[20:21], off
	global_load_dwordx4 v[208:211], v[20:21], off offset:16
	s_waitcnt lgkmcnt(0)
	s_barrier
	v_cndmask_b32_e32 v4, v194, v4, vcc
	v_lshlrev_b32_e32 v0, 3, v1
	v_and_b32_e32 v2, 0x78, v0
	v_lshlrev_b32_e32 v10, 2, v4
	v_xor_b32_e32 v4, 8, v194
	v_lshl_add_u32 v0, v2, 2, 16
	v_or_b32_e32 v2, s21, v2
	v_cmp_lt_i32_e32 vcc, v4, v195
	s_ashr_i32 s21, s20, 31
	v_ashrrev_i32_e32 v3, 31, v2
	v_cndmask_b32_e32 v4, v194, v4, vcc
	s_lshl_b64 s[20:21], s[20:21], 16
	v_lshlrev_b32_e32 v11, 2, v4
	s_add_u32 s20, s2, s20
	v_lshlrev_b64 v[4:5], 2, v[2:3]
	s_addc_u32 s21, s26, s21
	v_lshl_add_u64 v[2:3], s[8:9], 0, v[4:5]
	v_lshl_add_u64 v[4:5], s[10:11], 0, v[4:5]
; __device__ __forceinline__ int ltid() { int t = threadIdx.x; asm volatile("" : "+v"(t)); return t; }
; template <class Epi>
; __device__ __forceinline__ void epilogue_rows(f32x16 (&acc)[2][2], int m0, int n0, unsigned char* smem, Epi epi) {
;     ...
;   for (int it = 0; it < 8; ++it) {
;     int idx = tid + 256 * it; int r = idx >> 4, c8 = (idx & 15) * 8;
;     float4 a = *(const float4*)(sC + r * 132 + c8), b = *(const float4*)(sC + r * 132 + c8 + 4);
;     epi(m0 + r, n0 + c8, a, b);
;   }
; __device__ __forceinline__ void phase6(const Params& p, unsigned char* smem) {
;     ...
;     epilogue_rows(acc, m0, n0, smem, [&](int m, int n, float4 a, float4 b) {
;       const float4* xp = (const float4*)(p.x + (size_t)m * 1024 + n);
;       float4 x0 = xp[0], x1 = xp[1];
;       a.x += x0.x; a.y += x0.y; a.z += x0.z; a.w += x0.w; b.x += x1.x; b.y += x1.y; b.z += x1.z; b.w += x1.w;
;       float4* op = (float4*)(p.out + (size_t)m * 1024 + n);
;       op[0] = a; op[1] = b;
;       float sq = a.x * a.x + a.y * a.y + a.z * a.z + a.w * a.w + b.x * b.x + b.y * b.y + b.z * b.z + b.w * b.w;
;       sq += __shfl_xor(sq, 1); sq += __shfl_xor(sq, 2); sq += __shfl_xor(sq, 4); sq += __shfl_xor(sq, 8);
;       if ((ltid() & 15) == 0) PSUM[(size_t)nt * NX + m] = sq;
.LBB0_437:
	s_waitcnt vmcnt(0)
	v_add_u32_e32 v12, s24, v1
	s_waitcnt lgkmcnt(0)
	v_ashrrev_i32_e32 v13, 4, v12
	v_add_u32_e32 v6, s38, v13
	v_ashrrev_i32_e32 v7, 31, v6
	v_lshlrev_b64 v[30:31], 12, v[6:7]
	v_lshl_add_u64 v[22:23], v[2:3], 0, v[30:31]
	v_mov_b32_e32 v14, v144
	v_mov_b32_e32 v15, v145
	v_mov_b32_e32 v16, v146
	v_mov_b32_e32 v17, v147
	v_mov_b32_e32 v18, v148
	v_mov_b32_e32 v19, v149
	v_mov_b32_e32 v20, v150
	v_mov_b32_e32 v21, v151
	v_mad_u64_u32 v[26:27], s[22:23], v13, s35, v[0:1]
	v_mov_b32_e32 v140, v26
	ds_read_b128 v[22:25], v26
	ds_read_b128 v[26:29], v26 offset:16
	s_waitcnt lgkmcnt(1)
	v_pk_add_f32 v[14:15], v[22:23], v[14:15]
	v_pk_add_f32 v[16:17], v[24:25], v[16:17]
	v_pk_mul_f32 v[22:23], v[14:15], v[14:15]
	v_pk_mul_f32 v[24:25], v[16:17], v[16:17]
	v_add_f32_e32 v13, v22, v23
	s_waitcnt lgkmcnt(0)
	v_pk_add_f32 v[18:19], v[26:27], v[18:19]
	v_add_f32_e32 v13, v13, v24
	v_pk_mul_f32 v[26:27], v[18:19], v[18:19]
	v_add_f32_e32 v13, v13, v25
	v_pk_add_f32 v[20:21], v[28:29], v[20:21]
	v_add_f32_e32 v13, v13, v26
	v_pk_mul_f32 v[28:29], v[20:21], v[20:21]
	v_add_f32_e32 v13, v13, v27
	v_add_f32_e32 v13, v13, v28
	v_add_f32_e32 v13, v13, v29
	ds_bpermute_b32 v22, v8, v13
	s_waitcnt lgkmcnt(0)
	v_add_f32_e32 v13, v13, v22
	ds_bpermute_b32 v22, v9, v13
	s_waitcnt lgkmcnt(0)
	v_add_f32_e32 v13, v13, v22
	ds_bpermute_b32 v24, v10, v13
	v_lshl_add_u64 v[22:23], v[4:5], 0, v[30:31]
	ds_write_b128 v140, v[14:17]
	ds_write_b128 v140, v[18:21] offset:16
	s_waitcnt lgkmcnt(0)
	v_add_f32_e32 v13, v13, v24
	ds_bpermute_b32 v14, v11, v13
	v_mov_b32_e32 v15, v218
	s_nop 0
	v_and_b32_e32 v15, 15, v15
	v_cmp_eq_u32_e32 vcc, 0, v15
	s_and_saveexec_b64 s[22:23], vcc
	s_cbranch_execz .Lepi_p6_0_0
	s_waitcnt lgkmcnt(0)
	v_add_f32_e32 v13, v13, v14
	v_lshl_add_u64 v[6:7], v[6:7], 2, s[20:21]
	global_store_dword v[6:7], v13, off sc1
.Lepi_p6_0_0:
	s_or_b64 exec, exec, s[22:23]
	v_add_u32_e32 v6, 0x100, v12
	v_ashrrev_i32_e32 v22, 4, v6
	v_add_u32_e32 v6, s38, v22
	v_ashrrev_i32_e32 v7, 31, v6
	v_lshlrev_b64 v[28:29], 12, v[6:7]
	v_lshl_add_u64 v[20:21], v[2:3], 0, v[28:29]
	s_waitcnt lgkmcnt(0)
	v_mov_b32_e32 v12, v152
	v_mov_b32_e32 v13, v153
	v_mov_b32_e32 v14, v154
	v_mov_b32_e32 v15, v155
	v_mov_b32_e32 v16, v156
	v_mov_b32_e32 v17, v157
	v_mov_b32_e32 v18, v158
	v_mov_b32_e32 v19, v159
	v_mad_u64_u32 v[24:25], s[22:23], v22, s35, v[0:1]
	v_mov_b32_e32 v141, v24
	ds_read_b128 v[20:23], v24
	ds_read_b128 v[24:27], v24 offset:16
	s_waitcnt lgkmcnt(1)
	v_pk_add_f32 v[12:13], v[20:21], v[12:13]
	v_pk_add_f32 v[14:15], v[22:23], v[14:15]
	v_pk_mul_f32 v[20:21], v[12:13], v[12:13]
	v_pk_mul_f32 v[22:23], v[14:15], v[14:15]
	v_add_f32_e32 v20, v20, v21
	s_waitcnt lgkmcnt(0)
	v_pk_add_f32 v[16:17], v[24:25], v[16:17]
	v_add_f32_e32 v20, v20, v22
	v_pk_mul_f32 v[24:25], v[16:17], v[16:17]
	v_add_f32_e32 v20, v20, v23
	v_pk_add_f32 v[18:19], v[26:27], v[18:19]
	v_add_f32_e32 v20, v20, v24
	v_pk_mul_f32 v[26:27], v[18:19], v[18:19]
	v_add_f32_e32 v20, v20, v25
	v_add_f32_e32 v20, v20, v26
	v_add_f32_e32 v20, v20, v27
	ds_bpermute_b32 v21, v8, v20
	s_waitcnt lgkmcnt(0)
	v_add_f32_e32 v20, v20, v21
	ds_bpermute_b32 v21, v9, v20
	s_waitcnt lgkmcnt(0)
	v_add_f32_e32 v22, v20, v21
	ds_bpermute_b32 v23, v10, v22
	v_lshl_add_u64 v[20:21], v[4:5], 0, v[28:29]
	ds_write_b128 v141, v[12:15]
	ds_write_b128 v141, v[16:19] offset:16
	s_nop 0
	v_mov_b32_e32 v14, v218
	s_waitcnt lgkmcnt(0)
	v_add_f32_e32 v12, v22, v23
	ds_bpermute_b32 v13, v11, v12
	s_nop 0
	v_and_b32_e32 v14, 15, v14
	v_cmp_eq_u32_e32 vcc, 0, v14
	s_and_saveexec_b64 s[22:23], vcc
	s_cbranch_execz .Lepi_p6_0_latch
	s_waitcnt lgkmcnt(0)
	v_add_f32_e32 v12, v12, v13
	v_lshl_add_u64 v[6:7], v[6:7], 2, s[20:21]
	global_store_dword v[6:7], v12, off sc1
.Lepi_p6_0_latch:
	s_or_b64 exec, exec, s[22:23]
	s_addk_i32 s24, 0x200
	v_add_u32_e32 v12, s24, v1
	s_waitcnt lgkmcnt(0)
	v_ashrrev_i32_e32 v13, 4, v12
	v_add_u32_e32 v6, s38, v13
	v_ashrrev_i32_e32 v7, 31, v6
	v_lshlrev_b64 v[30:31], 12, v[6:7]
	v_lshl_add_u64 v[22:23], v[2:3], 0, v[30:31]
	v_mov_b32_e32 v14, v160
	v_mov_b32_e32 v15, v161
	v_mov_b32_e32 v16, v162
	v_mov_b32_e32 v17, v163
	v_mov_b32_e32 v18, v164
	v_mov_b32_e32 v19, v165
	v_mov_b32_e32 v20, v166
	v_mov_b32_e32 v21, v167
	v_mad_u64_u32 v[26:27], s[22:23], v13, s35, v[0:1]
	v_mov_b32_e32 v140, v26
	ds_read_b128 v[22:25], v26
	ds_read_b128 v[26:29], v26 offset:16
	s_waitcnt lgkmcnt(1)
	v_pk_add_f32 v[14:15], v[22:23], v[14:15]
	v_pk_add_f32 v[16:17], v[24:25], v[16:17]
	v_pk_mul_f32 v[22:23], v[14:15], v[14:15]
	v_pk_mul_f32 v[24:25], v[16:17], v[16:17]
	v_add_f32_e32 v13, v22, v23
	s_waitcnt lgkmcnt(0)
	v_pk_add_f32 v[18:19], v[26:27], v[18:19]
	v_add_f32_e32 v13, v13, v24
	v_pk_mul_f32 v[26:27], v[18:19], v[18:19]
	v_add_f32_e32 v13, v13, v25
	v_pk_add_f32 v[20:21], v[28:29], v[20:21]
	v_add_f32_e32 v13, v13, v26
	v_pk_mul_f32 v[28:29], v[20:21], v[20:21]
	v_add_f32_e32 v13, v13, v27
	v_add_f32_e32 v13, v13, v28
	v_add_f32_e32 v13, v13, v29
	ds_bpermute_b32 v22, v8, v13
	s_waitcnt lgkmcnt(0)
	v_add_f32_e32 v13, v13, v22
	ds_bpermute_b32 v22, v9, v13
	s_waitcnt lgkmcnt(0)
	v_add_f32_e32 v13, v13, v22
	ds_bpermute_b32 v24, v10, v13
	v_lshl_add_u64 v[22:23], v[4:5], 0, v[30:31]
	ds_write_b128 v140, v[14:17]
	ds_write_b128 v140, v[18:21] offset:16
	s_waitcnt lgkmcnt(0)
	v_add_f32_e32 v13, v13, v24
	ds_bpermute_b32 v14, v11, v13
	v_mov_b32_e32 v15, v218
	s_nop 0
	v_and_b32_e32 v15, 15, v15
	v_cmp_eq_u32_e32 vcc, 0, v15
	s_and_saveexec_b64 s[22:23], vcc
	s_cbranch_execz .Lepi_p6_1_0
	s_waitcnt lgkmcnt(0)
	v_add_f32_e32 v13, v13, v14
	v_lshl_add_u64 v[6:7], v[6:7], 2, s[20:21]
	global_store_dword v[6:7], v13, off sc1
; __device__ __forceinline__ int ltid() { int t = threadIdx.x; asm volatile("" : "+v"(t)); return t; }
; __device__ __forceinline__ void phase6(const Params& p, unsigned char* smem) {
;     ...
;     epilogue_rows(acc, m0, n0, smem, [&](int m, int n, float4 a, float4 b) {
;       const float4* xp = (const float4*)(p.x + (size_t)m * 1024 + n);
;       float4 x0 = xp[0], x1 = xp[1];
;       a.x += x0.x; a.y += x0.y; a.z += x0.z; a.w += x0.w; b.x += x1.x; b.y += x1.y; b.z += x1.z; b.w += x1.w;
;       float4* op = (float4*)(p.out + (size_t)m * 1024 + n);
;       op[0] = a; op[1] = b;
;       float sq = a.x * a.x + a.y * a.y + a.z * a.z + a.w * a.w + b.x * b.x + b.y * b.y + b.z * b.z + b.w * b.w;
;       sq += __shfl_xor(sq, 1); sq += __shfl_xor(sq, 2); sq += __shfl_xor(sq, 4); sq += __shfl_xor(sq, 8);
;       if ((ltid() & 15) == 0) PSUM[(size_t)nt * NX + m] = sq;
.Lepi_p6_1_0:
	s_or_b64 exec, exec, s[22:23]
	v_add_u32_e32 v6, 0x100, v12
	v_ashrrev_i32_e32 v22, 4, v6
	v_add_u32_e32 v6, s38, v22
	v_ashrrev_i32_e32 v7, 31, v6
	v_lshlrev_b64 v[28:29], 12, v[6:7]
	v_lshl_add_u64 v[20:21], v[2:3], 0, v[28:29]
	s_waitcnt lgkmcnt(0)
	v_mov_b32_e32 v12, v168
	v_mov_b32_e32 v13, v169
	v_mov_b32_e32 v14, v170
	v_mov_b32_e32 v15, v171
	v_mov_b32_e32 v16, v172
	v_mov_b32_e32 v17, v173
	v_mov_b32_e32 v18, v174
	v_mov_b32_e32 v19, v175
	v_mad_u64_u32 v[24:25], s[22:23], v22, s35, v[0:1]
	v_mov_b32_e32 v141, v24
	ds_read_b128 v[20:23], v24
	ds_read_b128 v[24:27], v24 offset:16
	s_waitcnt lgkmcnt(1)
	v_pk_add_f32 v[12:13], v[20:21], v[12:13]
	v_pk_add_f32 v[14:15], v[22:23], v[14:15]
	v_pk_mul_f32 v[20:21], v[12:13], v[12:13]
	v_pk_mul_f32 v[22:23], v[14:15], v[14:15]
	v_add_f32_e32 v20, v20, v21
	s_waitcnt lgkmcnt(0)
	v_pk_add_f32 v[16:17], v[24:25], v[16:17]
	v_add_f32_e32 v20, v20, v22
	v_pk_mul_f32 v[24:25], v[16:17], v[16:17]
	v_add_f32_e32 v20, v20, v23
	v_pk_add_f32 v[18:19], v[26:27], v[18:19]
	v_add_f32_e32 v20, v20, v24
	v_pk_mul_f32 v[26:27], v[18:19], v[18:19]
	v_add_f32_e32 v20, v20, v25
	v_add_f32_e32 v20, v20, v26
	v_add_f32_e32 v20, v20, v27
	ds_bpermute_b32 v21, v8, v20
	s_waitcnt lgkmcnt(0)
	v_add_f32_e32 v20, v20, v21
	ds_bpermute_b32 v21, v9, v20
	s_waitcnt lgkmcnt(0)
	v_add_f32_e32 v22, v20, v21
	ds_bpermute_b32 v23, v10, v22
	v_lshl_add_u64 v[20:21], v[4:5], 0, v[28:29]
	ds_write_b128 v141, v[12:15]
	ds_write_b128 v141, v[16:19] offset:16
	s_nop 0
	v_mov_b32_e32 v14, v218
	s_waitcnt lgkmcnt(0)
	v_add_f32_e32 v12, v22, v23
	ds_bpermute_b32 v13, v11, v12
	s_nop 0
	v_and_b32_e32 v14, 15, v14
	v_cmp_eq_u32_e32 vcc, 0, v14
	s_and_saveexec_b64 s[22:23], vcc
	s_cbranch_execz .Lepi_p6_1_latch
	s_waitcnt lgkmcnt(0)
	v_add_f32_e32 v12, v12, v13
	v_lshl_add_u64 v[6:7], v[6:7], 2, s[20:21]
	global_store_dword v[6:7], v12, off sc1
.Lepi_p6_1_latch:
	s_or_b64 exec, exec, s[22:23]
	s_addk_i32 s24, 0x200
	v_add_u32_e32 v12, s24, v1
	s_waitcnt lgkmcnt(0)
	v_ashrrev_i32_e32 v13, 4, v12
	v_add_u32_e32 v6, s38, v13
	v_ashrrev_i32_e32 v7, 31, v6
	v_lshlrev_b64 v[30:31], 12, v[6:7]
	v_lshl_add_u64 v[22:23], v[2:3], 0, v[30:31]
	v_mov_b32_e32 v14, v176
	v_mov_b32_e32 v15, v177
	v_mov_b32_e32 v16, v178
	v_mov_b32_e32 v17, v179
	v_mov_b32_e32 v18, v180
	v_mov_b32_e32 v19, v181
	v_mov_b32_e32 v20, v182
	v_mov_b32_e32 v21, v183
	v_mad_u64_u32 v[26:27], s[22:23], v13, s35, v[0:1]
	v_mov_b32_e32 v140, v26
	ds_read_b128 v[22:25], v26
	ds_read_b128 v[26:29], v26 offset:16
	s_waitcnt lgkmcnt(1)
	v_pk_add_f32 v[14:15], v[22:23], v[14:15]
	v_pk_add_f32 v[16:17], v[24:25], v[16:17]
	v_pk_mul_f32 v[22:23], v[14:15], v[14:15]
	v_pk_mul_f32 v[24:25], v[16:17], v[16:17]
	v_add_f32_e32 v13, v22, v23
	s_waitcnt lgkmcnt(0)
	v_pk_add_f32 v[18:19], v[26:27], v[18:19]
	v_add_f32_e32 v13, v13, v24
	v_pk_mul_f32 v[26:27], v[18:19], v[18:19]
	v_add_f32_e32 v13, v13, v25
	v_pk_add_f32 v[20:21], v[28:29], v[20:21]
	v_add_f32_e32 v13, v13, v26
	v_pk_mul_f32 v[28:29], v[20:21], v[20:21]
	v_add_f32_e32 v13, v13, v27
	v_add_f32_e32 v13, v13, v28
	v_add_f32_e32 v13, v13, v29
	ds_bpermute_b32 v22, v8, v13
	s_waitcnt lgkmcnt(0)
	v_add_f32_e32 v13, v13, v22
	ds_bpermute_b32 v22, v9, v13
	s_waitcnt lgkmcnt(0)
	v_add_f32_e32 v13, v13, v22
	ds_bpermute_b32 v24, v10, v13
	v_lshl_add_u64 v[22:23], v[4:5], 0, v[30:31]
	ds_write_b128 v140, v[14:17]
	ds_write_b128 v140, v[18:21] offset:16
	s_waitcnt lgkmcnt(0)
	v_add_f32_e32 v13, v13, v24
	ds_bpermute_b32 v14, v11, v13
	v_mov_b32_e32 v15, v218
	s_nop 0
	v_and_b32_e32 v15, 15, v15
	v_cmp_eq_u32_e32 vcc, 0, v15
	s_and_saveexec_b64 s[22:23], vcc
	s_cbranch_execz .Lepi_p6_2_0
	s_waitcnt lgkmcnt(0)
	v_add_f32_e32 v13, v13, v14
	v_lshl_add_u64 v[6:7], v[6:7], 2, s[20:21]
	global_store_dword v[6:7], v13, off sc1
.Lepi_p6_2_0:
	s_or_b64 exec, exec, s[22:23]
	v_add_u32_e32 v6, 0x100, v12
	v_ashrrev_i32_e32 v22, 4, v6
	v_add_u32_e32 v6, s38, v22
	v_ashrrev_i32_e32 v7, 31, v6
	v_lshlrev_b64 v[28:29], 12, v[6:7]
	v_lshl_add_u64 v[20:21], v[2:3], 0, v[28:29]
	s_waitcnt lgkmcnt(0)
	v_mov_b32_e32 v12, v184
	v_mov_b32_e32 v13, v185
	v_mov_b32_e32 v14, v186
	v_mov_b32_e32 v15, v187
	v_mov_b32_e32 v16, v188
	v_mov_b32_e32 v17, v189
	v_mov_b32_e32 v18, v190
	v_mov_b32_e32 v19, v191
	v_mad_u64_u32 v[24:25], s[22:23], v22, s35, v[0:1]
	v_mov_b32_e32 v141, v24
	ds_read_b128 v[20:23], v24
	ds_read_b128 v[24:27], v24 offset:16
	s_waitcnt lgkmcnt(1)
	v_pk_add_f32 v[12:13], v[20:21], v[12:13]
	v_pk_add_f32 v[14:15], v[22:23], v[14:15]
	v_pk_mul_f32 v[20:21], v[12:13], v[12:13]
	v_pk_mul_f32 v[22:23], v[14:15], v[14:15]
	v_add_f32_e32 v20, v20, v21
	s_waitcnt lgkmcnt(0)
	v_pk_add_f32 v[16:17], v[24:25], v[16:17]
	v_add_f32_e32 v20, v20, v22
	v_pk_mul_f32 v[24:25], v[16:17], v[16:17]
	v_add_f32_e32 v20, v20, v23
	v_pk_add_f32 v[18:19], v[26:27], v[18:19]
	v_add_f32_e32 v20, v20, v24
	v_pk_mul_f32 v[26:27], v[18:19], v[18:19]
	v_add_f32_e32 v20, v20, v25
	v_add_f32_e32 v20, v20, v26
	v_add_f32_e32 v20, v20, v27
	ds_bpermute_b32 v21, v8, v20
	s_waitcnt lgkmcnt(0)
	v_add_f32_e32 v20, v20, v21
	ds_bpermute_b32 v21, v9, v20
	s_waitcnt lgkmcnt(0)
	v_add_f32_e32 v22, v20, v21
	ds_bpermute_b32 v23, v10, v22
	v_lshl_add_u64 v[20:21], v[4:5], 0, v[28:29]
	ds_write_b128 v141, v[12:15]
	ds_write_b128 v141, v[16:19] offset:16
	s_nop 0
	v_mov_b32_e32 v14, v218
	s_waitcnt lgkmcnt(0)
	v_add_f32_e32 v12, v22, v23
	ds_bpermute_b32 v13, v11, v12
	s_nop 0
	v_and_b32_e32 v14, 15, v14
	v_cmp_eq_u32_e32 vcc, 0, v14
	s_and_saveexec_b64 s[22:23], vcc
	s_cbranch_execz .Lepi_p6_2_latch
	s_waitcnt lgkmcnt(0)
	v_add_f32_e32 v12, v12, v13
	v_lshl_add_u64 v[6:7], v[6:7], 2, s[20:21]
	global_store_dword v[6:7], v12, off sc1
; __device__ __forceinline__ int ltid() { int t = threadIdx.x; asm volatile("" : "+v"(t)); return t; }
; __device__ __forceinline__ void phase6(const Params& p, unsigned char* smem) {
;     ...
;     epilogue_rows(acc, m0, n0, smem, [&](int m, int n, float4 a, float4 b) {
;       const float4* xp = (const float4*)(p.x + (size_t)m * 1024 + n);
;       float4 x0 = xp[0], x1 = xp[1];
;       a.x += x0.x; a.y += x0.y; a.z += x0.z; a.w += x0.w; b.x += x1.x; b.y += x1.y; b.z += x1.z; b.w += x1.w;
;       float4* op = (float4*)(p.out + (size_t)m * 1024 + n);
;       op[0] = a; op[1] = b;
;       float sq = a.x * a.x + a.y * a.y + a.z * a.z + a.w * a.w + b.x * b.x + b.y * b.y + b.z * b.z + b.w * b.w;
;       sq += __shfl_xor(sq, 1); sq += __shfl_xor(sq, 2); sq += __shfl_xor(sq, 4); sq += __shfl_xor(sq, 8);
;       if ((ltid() & 15) == 0) PSUM[(size_t)nt * NX + m] = sq;
.Lepi_p6_2_latch:
	s_or_b64 exec, exec, s[22:23]
	s_addk_i32 s24, 0x200
	v_add_u32_e32 v12, s24, v1
	s_waitcnt lgkmcnt(0)
	v_ashrrev_i32_e32 v13, 4, v12
	v_add_u32_e32 v6, s38, v13
	v_ashrrev_i32_e32 v7, 31, v6
	v_lshlrev_b64 v[30:31], 12, v[6:7]
	v_lshl_add_u64 v[22:23], v[2:3], 0, v[30:31]
	v_mov_b32_e32 v14, v196
	v_mov_b32_e32 v15, v197
	v_mov_b32_e32 v16, v198
	v_mov_b32_e32 v17, v199
	v_mov_b32_e32 v18, v200
	v_mov_b32_e32 v19, v201
	v_mov_b32_e32 v20, v202
	v_mov_b32_e32 v21, v203
	v_mad_u64_u32 v[26:27], s[22:23], v13, s35, v[0:1]
	v_mov_b32_e32 v140, v26
	ds_read_b128 v[22:25], v26
	ds_read_b128 v[26:29], v26 offset:16
	s_waitcnt lgkmcnt(1)
	v_pk_add_f32 v[14:15], v[22:23], v[14:15]
	v_pk_add_f32 v[16:17], v[24:25], v[16:17]
	v_pk_mul_f32 v[22:23], v[14:15], v[14:15]
	v_pk_mul_f32 v[24:25], v[16:17], v[16:17]
	v_add_f32_e32 v13, v22, v23
	s_waitcnt lgkmcnt(0)
	v_pk_add_f32 v[18:19], v[26:27], v[18:19]
	v_add_f32_e32 v13, v13, v24
	v_pk_mul_f32 v[26:27], v[18:19], v[18:19]
	v_add_f32_e32 v13, v13, v25
	v_pk_add_f32 v[20:21], v[28:29], v[20:21]
	v_add_f32_e32 v13, v13, v26
	v_pk_mul_f32 v[28:29], v[20:21], v[20:21]
	v_add_f32_e32 v13, v13, v27
	v_add_f32_e32 v13, v13, v28
	v_add_f32_e32 v13, v13, v29
	ds_bpermute_b32 v22, v8, v13
	s_waitcnt lgkmcnt(0)
	v_add_f32_e32 v13, v13, v22
	ds_bpermute_b32 v22, v9, v13
	s_waitcnt lgkmcnt(0)
	v_add_f32_e32 v13, v13, v22
	ds_bpermute_b32 v24, v10, v13
	v_lshl_add_u64 v[22:23], v[4:5], 0, v[30:31]
	ds_write_b128 v140, v[14:17]
	ds_write_b128 v140, v[18:21] offset:16
	s_waitcnt lgkmcnt(0)
	v_add_f32_e32 v13, v13, v24
	ds_bpermute_b32 v14, v11, v13
	v_mov_b32_e32 v15, v218
	s_nop 0
	v_and_b32_e32 v15, 15, v15
	v_cmp_eq_u32_e32 vcc, 0, v15
	s_and_saveexec_b64 s[22:23], vcc
	s_cbranch_execz .Lepi_p6_3_0
	s_waitcnt lgkmcnt(0)
	v_add_f32_e32 v13, v13, v14
	v_lshl_add_u64 v[6:7], v[6:7], 2, s[20:21]
	global_store_dword v[6:7], v13, off sc1
.Lepi_p6_3_0:
	s_or_b64 exec, exec, s[22:23]
	v_add_u32_e32 v6, 0x100, v12
	v_ashrrev_i32_e32 v22, 4, v6
	v_add_u32_e32 v6, s38, v22
	v_ashrrev_i32_e32 v7, 31, v6
	v_lshlrev_b64 v[28:29], 12, v[6:7]
	v_lshl_add_u64 v[20:21], v[2:3], 0, v[28:29]
	s_waitcnt lgkmcnt(0)
	v_mov_b32_e32 v12, v204
	v_mov_b32_e32 v13, v205
	v_mov_b32_e32 v14, v206
	v_mov_b32_e32 v15, v207
	v_mov_b32_e32 v16, v208
	v_mov_b32_e32 v17, v209
	v_mov_b32_e32 v18, v210
	v_mov_b32_e32 v19, v211
	v_mad_u64_u32 v[24:25], s[22:23], v22, s35, v[0:1]
	v_mov_b32_e32 v141, v24
	ds_read_b128 v[20:23], v24
	ds_read_b128 v[24:27], v24 offset:16
	s_waitcnt lgkmcnt(1)
	v_pk_add_f32 v[12:13], v[20:21], v[12:13]
	v_pk_add_f32 v[14:15], v[22:23], v[14:15]
	v_pk_mul_f32 v[20:21], v[12:13], v[12:13]
	v_pk_mul_f32 v[22:23], v[14:15], v[14:15]
	v_add_f32_e32 v20, v20, v21
	s_waitcnt lgkmcnt(0)
	v_pk_add_f32 v[16:17], v[24:25], v[16:17]
	v_add_f32_e32 v20, v20, v22
	v_pk_mul_f32 v[24:25], v[16:17], v[16:17]
	v_add_f32_e32 v20, v20, v23
	v_pk_add_f32 v[18:19], v[26:27], v[18:19]
	v_add_f32_e32 v20, v20, v24
	v_pk_mul_f32 v[26:27], v[18:19], v[18:19]
	v_add_f32_e32 v20, v20, v25
	v_add_f32_e32 v20, v20, v26
	v_add_f32_e32 v20, v20, v27
	ds_bpermute_b32 v21, v8, v20
	s_waitcnt lgkmcnt(0)
	v_add_f32_e32 v20, v20, v21
	ds_bpermute_b32 v21, v9, v20
	s_waitcnt lgkmcnt(0)
	v_add_f32_e32 v22, v20, v21
	ds_bpermute_b32 v23, v10, v22
	v_lshl_add_u64 v[20:21], v[4:5], 0, v[28:29]
	ds_write_b128 v141, v[12:15]
	ds_write_b128 v141, v[16:19] offset:16
	s_nop 0
	v_mov_b32_e32 v14, v218
	s_waitcnt lgkmcnt(0)
	v_add_f32_e32 v12, v22, v23
	ds_bpermute_b32 v13, v11, v12
	s_nop 0
	v_and_b32_e32 v14, 15, v14
	v_cmp_eq_u32_e32 vcc, 0, v14
	s_and_saveexec_b64 s[22:23], vcc
	s_cbranch_execz .Lepi_p6_3_latch
	s_waitcnt lgkmcnt(0)
	v_add_f32_e32 v12, v12, v13
	v_lshl_add_u64 v[6:7], v[6:7], 2, s[20:21]
	global_store_dword v[6:7], v12, off sc1
.Lepi_p6_3_latch:
	s_or_b64 exec, exec, s[22:23]
	s_addk_i32 s24, 0x200
	s_branch .Lp6_norm
